# write-through (sc1) on bulk producer stores (pool, sample state, xprep, ssdnorm, scan y, in-proj epilogue) to shrink the barrier L2 write-back
# baseline (speedup 1.0000x reference)
.LBB0_233:
	s_load_dwordx4 s[24:27], s[88:89], 0x0
	v_add_u32_e32 v37, -1, v31
	v_cmp_gt_i32_e64 s[40:41], s20, v37
	v_add_u32_e32 v39, 0xffffbfff, v31
	v_cmp_gt_i32_e64 s[38:39], s20, v31
	v_lshlrev_b32_e32 v128, 2, v30
	global_load_dwordx4 v[238:241], v[32:33], off
	global_load_dwordx4 v[242:245], v[32:33], off offset:1024
	global_load_dwordx4 v[246:249], v[32:33], off offset:2048
	global_load_dwordx4 v[228:231], v[32:33], off offset:3072
	v_lshl_add_u64 v[16:17], v[28:29], 0, s[62:63]
	v_cndmask_b32_e64 v17, 0, v17, s[40:41]
	v_cndmask_b32_e64 v16, v39, v16, s[40:41]
	s_waitcnt lgkmcnt(0)
	v_mov_b32_e32 v20, s27
	v_mov_b32_e32 v21, s25
	v_mov_b32_e32 v22, s26
	v_mov_b32_e32 v23, s24
	v_cndmask_b32_e64 v19, v20, v21, s[40:41]
	v_cndmask_b32_e64 v18, v22, v23, s[40:41]
	v_lshlrev_b64 v[16:17], 12, v[16:17]
	v_lshl_add_u64 v[16:17], v[18:19], 0, v[16:17]
	v_lshl_add_u64 v[16:17], v[16:17], 0, v[128:129]
	global_load_dwordx4 v[0:3], v[16:17], off
	global_load_dwordx4 v[4:7], v[16:17], off offset:1024
	global_load_dwordx4 v[8:11], v[16:17], off offset:2048
	global_load_dwordx4 v[12:15], v[16:17], off offset:3072
	v_lshl_add_u64 v[16:17], v[44:45], 0, s[62:63]
	v_add_u32_e32 v18, 0xffffc000, v31
	v_cndmask_b32_e64 v17, 0, v17, s[38:39]
	v_cndmask_b32_e64 v16, v18, v16, s[38:39]
	v_cndmask_b32_e64 v19, v20, v21, s[38:39]
	v_cndmask_b32_e64 v18, v22, v23, s[38:39]
	v_lshlrev_b64 v[16:17], 12, v[16:17]
	v_lshl_add_u64 v[16:17], v[18:19], 0, v[16:17]
	v_lshl_add_u64 v[16:17], v[16:17], 0, v[128:129]
	global_load_dwordx4 v[20:23], v[16:17], off offset:1024
	global_load_dwordx4 v[24:27], v[16:17], off offset:2048
	global_load_dwordx4 v[50:53], v[16:17], off offset:3072
	global_load_dwordx4 v[16:19], v[16:17], off
	v_lshrrev_b32_e32 v39, 3, v39
	v_ashrrev_i32_e32 v37, 11, v37
	v_add_u32_e32 v39, 8, v39
	v_cndmask_b32_e64 v56, v39, v37, s[40:41]
	v_mov_b64_e32 v[54:55], s[84:85]
	v_mad_i64_i32 v[54:55], s[8:9], v56, s21, v[54:55]
	v_lshl_add_u64 v[54:55], v[54:55], 0, s[94:95]
	v_lshl_add_u64 v[54:55], v[54:55], 0, v[128:129]
	global_load_dwordx4 v[58:61], v[54:55], off offset:1024
	global_load_dwordx4 v[62:65], v[54:55], off offset:2048
	global_load_dwordx4 v[234:237], v[54:55], off offset:3072
	global_load_dwordx4 v[54:57], v[54:55], off
	s_add_u32 s28, s84, s19
	s_addc_u32 s29, s85, 0
	s_add_u32 s30, s84, s46
	s_addc_u32 s31, s85, 0
	s_waitcnt vmcnt(0)
	v_pk_add_f32 v[54:55], v[54:55], 1.0 op_sel_hi:[1,0]
	v_pk_add_f32 v[56:57], v[56:57], 1.0 op_sel_hi:[1,0]
	v_pk_add_f32 v[58:59], v[58:59], 1.0 op_sel_hi:[1,0]
	v_pk_add_f32 v[60:61], v[60:61], 1.0 op_sel_hi:[1,0]
	v_pk_add_f32 v[62:63], v[62:63], 1.0 op_sel_hi:[1,0]
	v_pk_add_f32 v[64:65], v[64:65], 1.0 op_sel_hi:[1,0]
	v_pk_add_f32 v[234:235], v[234:235], 1.0 op_sel_hi:[1,0]
	v_pk_add_f32 v[236:237], v[236:237], 1.0 op_sel_hi:[1,0]
	v_mul_f32_e32 v250, v1, v1
	v_mul_f32_e32 v251, v3, v3
	v_fmac_f32_e32 v250, v0, v0
	v_fmac_f32_e32 v251, v2, v2
	v_pk_mul_f32 v[66:67], v[0:1], v[238:239]
	v_add_f32_e32 v68, v250, v251
	v_pk_mul_f32 v[250:251], v[2:3], v[240:241]
	v_pk_mul_f32 v[66:67], v[54:55], v[66:67]
	v_pk_mul_f32 v[250:251], v[56:57], v[250:251]
	v_cvt_pk_bf16_f32 v66, v66, v67
	v_cvt_pk_bf16_f32 v67, v250, v251
	global_store_dwordx2 v48, v[66:67], s[28:29] offset:0 sc1
	v_cvt_pk_bf16_f32 v0, v0, v1
	v_cvt_pk_bf16_f32 v1, v2, v3
	global_store_dwordx2 v48, v[0:1], s[30:31] offset:0 sc1
	v_mul_f32_e32 v250, v5, v5
	v_mul_f32_e32 v251, v7, v7
	v_fmac_f32_e32 v250, v4, v4
	v_fmac_f32_e32 v251, v6, v6
	v_pk_mul_f32 v[66:67], v[4:5], v[242:243]
	v_add_f32_e32 v250, v250, v251
	v_add_f32_e32 v68, v68, v250
	v_pk_mul_f32 v[250:251], v[6:7], v[244:245]
	v_pk_mul_f32 v[66:67], v[58:59], v[66:67]
	v_pk_mul_f32 v[250:251], v[60:61], v[250:251]
	v_cvt_pk_bf16_f32 v66, v66, v67
	v_cvt_pk_bf16_f32 v67, v250, v251
	global_store_dwordx2 v48, v[66:67], s[28:29] offset:512 sc1
	v_cvt_pk_bf16_f32 v4, v4, v5
	v_cvt_pk_bf16_f32 v5, v6, v7
	global_store_dwordx2 v48, v[4:5], s[30:31] offset:512 sc1
	v_mul_f32_e32 v250, v9, v9
	v_mul_f32_e32 v251, v11, v11
	v_fmac_f32_e32 v250, v8, v8
	v_fmac_f32_e32 v251, v10, v10
	v_pk_mul_f32 v[66:67], v[8:9], v[246:247]
	v_add_f32_e32 v250, v250, v251
	v_add_f32_e32 v68, v68, v250
	v_pk_mul_f32 v[250:251], v[10:11], v[248:249]
	v_pk_mul_f32 v[66:67], v[62:63], v[66:67]
	v_pk_mul_f32 v[250:251], v[64:65], v[250:251]
	v_cvt_pk_bf16_f32 v66, v66, v67
	v_cvt_pk_bf16_f32 v67, v250, v251
	global_store_dwordx2 v48, v[66:67], s[28:29] offset:1024 sc1
	v_cvt_pk_bf16_f32 v8, v8, v9
	v_cvt_pk_bf16_f32 v9, v10, v11
	global_store_dwordx2 v48, v[8:9], s[30:31] offset:1024 sc1
	v_mul_f32_e32 v250, v13, v13
	v_mul_f32_e32 v251, v15, v15
	v_fmac_f32_e32 v250, v12, v12
	v_fmac_f32_e32 v251, v14, v14
	v_pk_mul_f32 v[66:67], v[12:13], v[228:229]
	v_add_f32_e32 v250, v250, v251
	v_add_f32_e32 v68, v68, v250
	v_pk_mul_f32 v[250:251], v[14:15], v[230:231]
	v_pk_mul_f32 v[66:67], v[234:235], v[66:67]
	v_pk_mul_f32 v[250:251], v[236:237], v[250:251]
	v_cvt_pk_bf16_f32 v66, v66, v67
	v_cvt_pk_bf16_f32 v67, v250, v251
	global_store_dwordx2 v48, v[66:67], s[28:29] offset:1536 sc1
	v_cvt_pk_bf16_f32 v12, v12, v13
	v_cvt_pk_bf16_f32 v13, v14, v15
	global_store_dwordx2 v48, v[12:13], s[30:31] offset:1536 sc1
	s_nop 1
	v_add_f32_dpp v68, v68, v68 quad_perm:[1,0,3,2] row_mask:0xf bank_mask:0xf
	s_nop 1
	v_add_f32_dpp v68, v68, v68 quad_perm:[2,3,0,1] row_mask:0xf bank_mask:0xf
	s_nop 1
	v_add_f32_dpp v68, v68, v68 row_half_mirror row_mask:0xf bank_mask:0xf
	s_nop 1
	v_add_f32_dpp v68, v68, v68 row_mirror row_mask:0xf bank_mask:0xf
	s_nop 1
	v_add_f32_dpp v68, v68, v68 row_bcast:15 row_mask:0xa bank_mask:0xf
	s_nop 1
	v_add_f32_dpp v68, v68, v68 row_bcast:31 row_mask:0xc bank_mask:0xf
	s_mov_b64 s[38:39], exec
	s_lshl_b64 s[40:41], 1, 63
	s_mov_b64 exec, s[40:41]
	v_lshl_add_u64 v[66:67], s[84:85], 0, v[46:47]
	global_store_dword v[66:67], v68, off sc1
	s_mov_b64 exec, s[38:39]
	v_mul_f32_e32 v250, v17, v17
	v_mul_f32_e32 v251, v19, v19
	v_fmac_f32_e32 v250, v16, v16
	v_fmac_f32_e32 v251, v18, v18
	v_pk_mul_f32 v[66:67], v[16:17], v[238:239]
	v_add_f32_e32 v68, v250, v251
	v_pk_mul_f32 v[250:251], v[18:19], v[240:241]
	v_pk_mul_f32 v[66:67], v[54:55], v[66:67]
	v_pk_mul_f32 v[250:251], v[56:57], v[250:251]
	v_cvt_pk_bf16_f32 v66, v66, v67
	v_cvt_pk_bf16_f32 v67, v250, v251
	global_store_dwordx2 v42, v[66:67], s[28:29] offset:2048 sc1
	v_cvt_pk_bf16_f32 v16, v16, v17
	v_cvt_pk_bf16_f32 v17, v18, v19
	global_store_dwordx2 v42, v[16:17], s[30:31] offset:2048 sc1
	v_mul_f32_e32 v250, v21, v21
	v_mul_f32_e32 v251, v23, v23
	v_fmac_f32_e32 v250, v20, v20
	v_fmac_f32_e32 v251, v22, v22
	v_pk_mul_f32 v[66:67], v[20:21], v[242:243]
	v_add_f32_e32 v250, v250, v251
	v_add_f32_e32 v68, v68, v250
	v_pk_mul_f32 v[250:251], v[22:23], v[244:245]
	v_pk_mul_f32 v[66:67], v[58:59], v[66:67]
	v_pk_mul_f32 v[250:251], v[60:61], v[250:251]
	v_cvt_pk_bf16_f32 v66, v66, v67
	v_cvt_pk_bf16_f32 v67, v250, v251
	global_store_dwordx2 v42, v[66:67], s[28:29] offset:2560 sc1
	v_cvt_pk_bf16_f32 v20, v20, v21
	v_cvt_pk_bf16_f32 v21, v22, v23
	global_store_dwordx2 v42, v[20:21], s[30:31] offset:2560 sc1
	v_mul_f32_e32 v250, v25, v25
	v_mul_f32_e32 v251, v27, v27
	v_fmac_f32_e32 v250, v24, v24
	v_fmac_f32_e32 v251, v26, v26
	v_pk_mul_f32 v[66:67], v[24:25], v[246:247]
	v_add_f32_e32 v250, v250, v251
	v_add_f32_e32 v68, v68, v250
	v_pk_mul_f32 v[250:251], v[26:27], v[248:249]
	v_pk_mul_f32 v[66:67], v[62:63], v[66:67]
	v_pk_mul_f32 v[250:251], v[64:65], v[250:251]
	v_cvt_pk_bf16_f32 v66, v66, v67
	v_cvt_pk_bf16_f32 v67, v250, v251
	global_store_dwordx2 v42, v[66:67], s[28:29] offset:3072 sc1
	v_cvt_pk_bf16_f32 v24, v24, v25
	v_cvt_pk_bf16_f32 v25, v26, v27
	global_store_dwordx2 v42, v[24:25], s[30:31] offset:3072 sc1
	v_mul_f32_e32 v250, v51, v51
	v_mul_f32_e32 v251, v53, v53
	v_fmac_f32_e32 v250, v50, v50
	v_fmac_f32_e32 v251, v52, v52
	v_pk_mul_f32 v[66:67], v[50:51], v[228:229]
	v_add_f32_e32 v250, v250, v251
	v_add_f32_e32 v68, v68, v250
	v_pk_mul_f32 v[250:251], v[52:53], v[230:231]
	v_pk_mul_f32 v[66:67], v[234:235], v[66:67]
	v_pk_mul_f32 v[250:251], v[236:237], v[250:251]
	v_cvt_pk_bf16_f32 v66, v66, v67
	v_cvt_pk_bf16_f32 v67, v250, v251
	global_store_dwordx2 v42, v[66:67], s[28:29] offset:3584 sc1
	v_cvt_pk_bf16_f32 v50, v50, v51
	v_cvt_pk_bf16_f32 v51, v52, v53
	global_store_dwordx2 v42, v[50:51], s[30:31] offset:3584 sc1
	s_nop 1
	v_add_f32_dpp v68, v68, v68 quad_perm:[1,0,3,2] row_mask:0xf bank_mask:0xf
	s_nop 1
	v_add_f32_dpp v68, v68, v68 quad_perm:[2,3,0,1] row_mask:0xf bank_mask:0xf
	s_nop 1
	v_add_f32_dpp v68, v68, v68 row_half_mirror row_mask:0xf bank_mask:0xf
	s_nop 1
	v_add_f32_dpp v68, v68, v68 row_mirror row_mask:0xf bank_mask:0xf
	s_nop 1
	v_add_f32_dpp v68, v68, v68 row_bcast:15 row_mask:0xa bank_mask:0xf
	s_nop 1
	v_add_f32_dpp v68, v68, v68 row_bcast:31 row_mask:0xc bank_mask:0xf
	s_mov_b64 s[38:39], exec
	s_lshl_b64 s[40:41], 1, 63
	s_mov_b64 exec, s[40:41]
	v_lshl_add_u64 v[66:67], s[84:85], 0, v[40:41]
	global_store_dword v[66:67], v68, off sc1
	s_mov_b64 exec, s[38:39]
	s_mov_b64 s[8:9], exec
	s_branch .LBB0_232

.LBB0_513:
	s_or_b64 exec, exec, s[10:11]
	v_lshl_add_u64 v[146:147], v[218:219], 2, s[60:61]
	global_load_dword v48, v[146:147], off
	global_load_dword v160, v[146:147], off offset:64
	global_load_dword v168, v[146:147], off offset:128
	global_load_dword v167, v[146:147], off offset:192
	global_load_dword v166, v[146:147], off offset:512
	global_load_dword v165, v[146:147], off offset:576
	global_load_dword v164, v[146:147], off offset:640
	global_load_dword v163, v[146:147], off offset:704
	v_lshlrev_b64 v[156:157], 7, v[218:219]
	s_waitcnt vmcnt(0)
	v_fmamk_f32 v48, v48, 0x3a800000, v234
	v_mul_f32_e32 v146, 0x4b800000, v48
	v_cmp_gt_f32_e32 vcc, s27, v48
	s_nop 1
	v_cndmask_b32_e32 v48, v48, v146, vcc
	v_rsq_f32_e32 v48, v48
	s_nop 0
	v_mul_f32_e32 v146, 0x45800000, v48
	v_cndmask_b32_e32 v158, v48, v146, vcc
	v_mov_b32_e32 v159, v158
	s_and_saveexec_b64 s[8:9], s[0:1]
	s_cbranch_execz .LBB0_519
	v_mov_b32_e32 v150, v158
	v_mov_b32_e32 v151, v158
	v_pk_fma_f32 v[148:149], v[128:129], v[150:151], v[144:145]
	v_pk_fma_f32 v[146:147], v[126:127], v[158:159], v[142:143]
	v_pk_fma_f32 v[152:153], v[124:125], v[150:151], v[140:141]
	v_pk_fma_f32 v[150:151], v[122:123], v[158:159], v[138:139]
	v_cmp_le_i32_e32 vcc, s21, v154
	s_and_saveexec_b64 s[10:11], vcc
	s_xor_b64 s[10:11], exec, s[10:11]
	s_cbranch_execz .LBB0_517
	s_andn2_b64 vcc, exec, s[68:69]
	s_cbranch_vccnz .LBB0_517
	v_lshl_add_u64 v[170:171], s[46:47], 0, v[156:157]
	v_subrev_u32_e32 v48, s21, v154
	v_lshl_add_u64 v[170:171], v[48:49], 2, v[170:171]
	global_store_dwordx4 v[170:171], v[146:149], off sc1
	global_store_dwordx4 v[170:171], v[150:153], off offset:16 sc1
.LBB0_517:
	s_andn2_saveexec_b64 s[10:11], s[10:11]
	s_cbranch_execz .LBB0_519
	v_cvt_pk_bf16_f32 v146, v146, v147
	v_cvt_pk_bf16_f32 v147, v148, v149
	v_cvt_pk_bf16_f32 v148, v150, v151
	v_mad_i64_i32 v[150:151], s[10:11], v218, s21, 0
	v_lshl_add_u64 v[150:151], v[150:151], 1, s[4:5]
	v_ashrrev_i32_e32 v155, 31, v154
	v_lshl_add_u64 v[150:151], v[154:155], 1, v[150:151]
	v_cvt_pk_bf16_f32 v149, v152, v153
	global_store_dwordx4 v[150:151], v[146:149], off sc1
.LBB0_519:
	s_or_b64 exec, exec, s[8:9]
	v_readlane_b32 s8, v252, 47
	s_nop 1
	v_cmp_gt_i32_e64 s[40:41], s8, v154
	s_and_saveexec_b64 s[42:43], s[40:41]
	s_cbranch_execz .LBB0_525
	v_mov_b32_e32 v150, v158
	v_mov_b32_e32 v151, v158
	v_pk_fma_f32 v[148:149], v[96:97], v[150:151], v[136:137]
	v_pk_fma_f32 v[146:147], v[94:95], v[158:159], v[134:135]
	v_pk_fma_f32 v[152:153], v[92:93], v[150:151], v[132:133]
	v_pk_fma_f32 v[150:151], v[90:91], v[158:159], v[130:131]
	v_cmp_le_i32_e32 vcc, s21, v162
	s_and_saveexec_b64 s[8:9], vcc
	s_xor_b64 s[8:9], exec, s[8:9]
	s_cbranch_execz .LBB0_523
	s_andn2_b64 vcc, exec, s[68:69]
	s_cbranch_vccnz .LBB0_523
	v_lshl_add_u64 v[156:157], s[46:47], 0, v[156:157]
	v_subrev_u32_e32 v48, s21, v162
	v_lshl_add_u64 v[156:157], v[48:49], 2, v[156:157]
	global_store_dwordx4 v[156:157], v[146:149], off sc1
	global_store_dwordx4 v[156:157], v[150:153], off offset:16 sc1
.LBB0_523:
	s_andn2_saveexec_b64 s[8:9], s[8:9]
	s_cbranch_execz .LBB0_525
	v_cvt_pk_bf16_f32 v146, v146, v147
	v_cvt_pk_bf16_f32 v147, v148, v149
	v_cvt_pk_bf16_f32 v148, v150, v151
	v_mad_i64_i32 v[150:151], s[8:9], v218, s21, 0
	v_lshl_add_u64 v[150:151], v[150:151], 1, s[4:5]
	v_ashrrev_i32_e32 v155, 31, v154
	v_lshl_add_u64 v[150:151], v[154:155], 1, v[150:151]
	v_cvt_pk_bf16_f32 v149, v152, v153
	global_store_dwordx4 v[150:151], v[146:149], off offset:256 sc1
.LBB0_525:
	s_or_b64 exec, exec, s[42:43]
	v_fmamk_f32 v48, v160, 0x3a800000, v234
	v_mul_f32_e32 v146, 0x4b800000, v48
	v_cmp_gt_f32_e32 vcc, s27, v48
	v_add_u32_e32 v156, 16, v218
	v_ashrrev_i32_e32 v157, 31, v156
	v_cndmask_b32_e32 v48, v48, v146, vcc
	v_rsq_f32_e32 v48, v48
	v_lshlrev_b64 v[158:159], 7, v[156:157]
	v_mul_f32_e32 v146, 0x45800000, v48
	v_cndmask_b32_e32 v160, v48, v146, vcc
	v_mov_b32_e32 v161, v160
	s_and_saveexec_b64 s[8:9], s[0:1]
	s_cbranch_execz .LBB0_531
	v_mov_b32_e32 v150, v160
	v_mov_b32_e32 v151, v160
	v_pk_fma_f32 v[148:149], v[120:121], v[150:151], v[144:145]
	v_pk_fma_f32 v[146:147], v[118:119], v[160:161], v[142:143]
	v_pk_fma_f32 v[152:153], v[116:117], v[150:151], v[140:141]
	v_pk_fma_f32 v[150:151], v[114:115], v[160:161], v[138:139]
	v_cmp_le_i32_e32 vcc, s21, v154
	s_and_saveexec_b64 s[10:11], vcc
	s_xor_b64 s[10:11], exec, s[10:11]
	s_cbranch_execz .LBB0_529
	s_andn2_b64 vcc, exec, s[68:69]
	s_cbranch_vccnz .LBB0_529
	v_lshl_add_u64 v[170:171], s[46:47], 0, v[158:159]
	v_subrev_u32_e32 v48, s21, v154
	v_lshl_add_u64 v[170:171], v[48:49], 2, v[170:171]
	global_store_dwordx4 v[170:171], v[146:149], off sc1
	global_store_dwordx4 v[170:171], v[150:153], off offset:16 sc1
.LBB0_529:
	s_andn2_saveexec_b64 s[10:11], s[10:11]
	s_cbranch_execz .LBB0_531
	v_cvt_pk_bf16_f32 v146, v146, v147
	v_cvt_pk_bf16_f32 v147, v148, v149
	v_cvt_pk_bf16_f32 v148, v150, v151
	v_mad_i64_i32 v[150:151], s[10:11], v156, s21, 0
	v_lshl_add_u64 v[150:151], v[150:151], 1, s[4:5]
	v_ashrrev_i32_e32 v155, 31, v154
	v_lshl_add_u64 v[150:151], v[154:155], 1, v[150:151]
	v_cvt_pk_bf16_f32 v149, v152, v153
	global_store_dwordx4 v[150:151], v[146:149], off sc1
.LBB0_531:
	s_or_b64 exec, exec, s[8:9]
	s_and_saveexec_b64 s[42:43], s[40:41]
	s_cbranch_execz .LBB0_537
	v_mov_b32_e32 v150, v160
	v_mov_b32_e32 v151, v160
	v_pk_fma_f32 v[148:149], v[88:89], v[150:151], v[136:137]
	v_pk_fma_f32 v[146:147], v[86:87], v[160:161], v[134:135]
	v_pk_fma_f32 v[152:153], v[84:85], v[150:151], v[132:133]
	v_pk_fma_f32 v[150:151], v[82:83], v[160:161], v[130:131]
	v_cmp_le_i32_e32 vcc, s21, v162
	s_and_saveexec_b64 s[8:9], vcc
	s_xor_b64 s[8:9], exec, s[8:9]
	s_cbranch_execz .LBB0_535
	s_andn2_b64 vcc, exec, s[68:69]
	s_cbranch_vccnz .LBB0_535
	v_lshl_add_u64 v[156:157], s[46:47], 0, v[158:159]
	v_subrev_u32_e32 v48, s21, v162
	v_lshl_add_u64 v[156:157], v[48:49], 2, v[156:157]
	global_store_dwordx4 v[156:157], v[146:149], off sc1
	global_store_dwordx4 v[156:157], v[150:153], off offset:16 sc1
.LBB0_535:
	s_andn2_saveexec_b64 s[8:9], s[8:9]
	s_cbranch_execz .LBB0_537
	v_cvt_pk_bf16_f32 v146, v146, v147
	v_cvt_pk_bf16_f32 v147, v148, v149
	v_cvt_pk_bf16_f32 v148, v150, v151
	v_mad_i64_i32 v[150:151], s[8:9], v156, s21, 0
	v_lshl_add_u64 v[150:151], v[150:151], 1, s[4:5]
	v_ashrrev_i32_e32 v155, 31, v154
	v_lshl_add_u64 v[150:151], v[154:155], 1, v[150:151]
	v_cvt_pk_bf16_f32 v149, v152, v153
	global_store_dwordx4 v[150:151], v[146:149], off offset:256 sc1
.LBB0_537:
	s_or_b64 exec, exec, s[42:43]
	v_fmamk_f32 v48, v168, 0x3a800000, v234
	v_mul_f32_e32 v146, 0x4b800000, v48
	v_cmp_gt_f32_e32 vcc, s27, v48
	v_add_u32_e32 v156, 32, v218
	v_ashrrev_i32_e32 v157, 31, v156
	v_cndmask_b32_e32 v48, v48, v146, vcc
	v_rsq_f32_e32 v48, v48
	v_lshlrev_b64 v[158:159], 7, v[156:157]
	v_mul_f32_e32 v146, 0x45800000, v48
	v_cndmask_b32_e32 v160, v48, v146, vcc
	v_mov_b32_e32 v161, v160
	s_and_saveexec_b64 s[8:9], s[0:1]
	s_cbranch_execz .LBB0_543
	v_mov_b32_e32 v150, v160
	v_mov_b32_e32 v151, v160
	v_pk_fma_f32 v[148:149], v[112:113], v[150:151], v[144:145]
	v_pk_fma_f32 v[146:147], v[110:111], v[160:161], v[142:143]
	v_pk_fma_f32 v[152:153], v[108:109], v[150:151], v[140:141]
	v_pk_fma_f32 v[150:151], v[106:107], v[160:161], v[138:139]
	v_cmp_le_i32_e32 vcc, s21, v154
	s_and_saveexec_b64 s[10:11], vcc
	s_xor_b64 s[10:11], exec, s[10:11]
	s_cbranch_execz .LBB0_541
	s_andn2_b64 vcc, exec, s[68:69]
	s_cbranch_vccnz .LBB0_541
	v_lshl_add_u64 v[168:169], s[46:47], 0, v[158:159]
	v_subrev_u32_e32 v48, s21, v154
	v_lshl_add_u64 v[168:169], v[48:49], 2, v[168:169]
	global_store_dwordx4 v[168:169], v[146:149], off sc1
	global_store_dwordx4 v[168:169], v[150:153], off offset:16 sc1

.LBB0_543:
	s_or_b64 exec, exec, s[8:9]
	s_and_saveexec_b64 s[42:43], s[40:41]
	s_cbranch_execz .LBB0_549
	v_mov_b32_e32 v150, v160
	v_mov_b32_e32 v151, v160
	v_pk_fma_f32 v[148:149], v[80:81], v[150:151], v[136:137]
	v_pk_fma_f32 v[146:147], v[78:79], v[160:161], v[134:135]
	v_pk_fma_f32 v[152:153], v[76:77], v[150:151], v[132:133]
	v_pk_fma_f32 v[150:151], v[74:75], v[160:161], v[130:131]
	v_cmp_le_i32_e32 vcc, s21, v162
	s_and_saveexec_b64 s[8:9], vcc
	s_xor_b64 s[8:9], exec, s[8:9]
	s_cbranch_execz .LBB0_547
	s_andn2_b64 vcc, exec, s[68:69]
	s_cbranch_vccnz .LBB0_547
	v_lshl_add_u64 v[156:157], s[46:47], 0, v[158:159]
	v_subrev_u32_e32 v48, s21, v162
	v_lshl_add_u64 v[156:157], v[48:49], 2, v[156:157]
	global_store_dwordx4 v[156:157], v[146:149], off sc1
	global_store_dwordx4 v[156:157], v[150:153], off offset:16 sc1

.LBB0_549:
	s_or_b64 exec, exec, s[42:43]
	v_fmamk_f32 v48, v167, 0x3a800000, v234
	v_mul_f32_e32 v146, 0x4b800000, v48
	v_cmp_gt_f32_e32 vcc, s27, v48
	v_add_u32_e32 v156, 48, v218
	v_ashrrev_i32_e32 v157, 31, v156
	v_cndmask_b32_e32 v48, v48, v146, vcc
	v_rsq_f32_e32 v48, v48
	v_lshlrev_b64 v[158:159], 7, v[156:157]
	v_mul_f32_e32 v146, 0x45800000, v48
	v_cndmask_b32_e32 v160, v48, v146, vcc
	v_mov_b32_e32 v161, v160
	s_and_saveexec_b64 s[8:9], s[0:1]
	s_cbranch_execz .LBB0_555
	v_mov_b32_e32 v150, v160
	v_mov_b32_e32 v151, v160
	v_pk_fma_f32 v[148:149], v[104:105], v[150:151], v[144:145]
	v_pk_fma_f32 v[146:147], v[102:103], v[160:161], v[142:143]
	v_pk_fma_f32 v[152:153], v[100:101], v[150:151], v[140:141]
	v_pk_fma_f32 v[150:151], v[98:99], v[160:161], v[138:139]
	v_cmp_le_i32_e32 vcc, s21, v154
	s_and_saveexec_b64 s[10:11], vcc
	s_xor_b64 s[10:11], exec, s[10:11]
	s_cbranch_execz .LBB0_553
	s_andn2_b64 vcc, exec, s[68:69]
	s_cbranch_vccnz .LBB0_553
	v_lshl_add_u64 v[168:169], s[46:47], 0, v[158:159]
	v_subrev_u32_e32 v48, s21, v154
	v_lshl_add_u64 v[168:169], v[48:49], 2, v[168:169]
	global_store_dwordx4 v[168:169], v[146:149], off sc1
	global_store_dwordx4 v[168:169], v[150:153], off offset:16 sc1

.LBB0_555:
	s_or_b64 exec, exec, s[8:9]
	s_and_saveexec_b64 s[42:43], s[40:41]
	s_cbranch_execz .LBB0_561
	v_mov_b32_e32 v150, v160
	v_mov_b32_e32 v151, v160
	v_pk_fma_f32 v[148:149], v[72:73], v[150:151], v[136:137]
	v_pk_fma_f32 v[146:147], v[70:71], v[160:161], v[134:135]
	v_pk_fma_f32 v[152:153], v[68:69], v[150:151], v[132:133]
	v_pk_fma_f32 v[150:151], v[66:67], v[160:161], v[130:131]
	v_cmp_le_i32_e32 vcc, s21, v162
	s_and_saveexec_b64 s[8:9], vcc
	s_xor_b64 s[8:9], exec, s[8:9]
	s_cbranch_execz .LBB0_559
	s_andn2_b64 vcc, exec, s[68:69]
	s_cbranch_vccnz .LBB0_559
	v_lshl_add_u64 v[156:157], s[46:47], 0, v[158:159]
	v_subrev_u32_e32 v48, s21, v162
	v_lshl_add_u64 v[156:157], v[48:49], 2, v[156:157]
	global_store_dwordx4 v[156:157], v[146:149], off sc1
	global_store_dwordx4 v[156:157], v[150:153], off offset:16 sc1

.LBB0_561:
	s_or_b64 exec, exec, s[42:43]
	v_fmamk_f32 v48, v166, 0x3a800000, v234
	v_mul_f32_e32 v146, 0x4b800000, v48
	v_cmp_gt_f32_e32 vcc, s27, v48
	v_add_u32_e32 v156, 0x80, v218
	v_ashrrev_i32_e32 v157, 31, v156
	v_cndmask_b32_e32 v48, v48, v146, vcc
	v_rsq_f32_e32 v48, v48
	v_lshlrev_b64 v[158:159], 7, v[156:157]
	v_mul_f32_e32 v146, 0x45800000, v48
	v_cndmask_b32_e32 v160, v48, v146, vcc
	v_mov_b32_e32 v161, v160
	s_and_saveexec_b64 s[8:9], s[0:1]
	s_cbranch_execz .LBB0_567
	v_mov_b32_e32 v150, v160
	v_mov_b32_e32 v151, v160
	v_pk_fma_f32 v[148:149], v[64:65], v[150:151], v[144:145]
	v_pk_fma_f32 v[146:147], v[62:63], v[160:161], v[142:143]
	v_pk_fma_f32 v[152:153], v[60:61], v[150:151], v[140:141]
	v_pk_fma_f32 v[150:151], v[58:59], v[160:161], v[138:139]
	v_cmp_le_i32_e32 vcc, s21, v154
	s_and_saveexec_b64 s[10:11], vcc
	s_xor_b64 s[10:11], exec, s[10:11]
	s_cbranch_execz .LBB0_565
	s_andn2_b64 vcc, exec, s[68:69]
	s_cbranch_vccnz .LBB0_565
	v_lshl_add_u64 v[166:167], s[46:47], 0, v[158:159]
	v_subrev_u32_e32 v48, s21, v154
	v_lshl_add_u64 v[166:167], v[48:49], 2, v[166:167]
	global_store_dwordx4 v[166:167], v[146:149], off sc1
	global_store_dwordx4 v[166:167], v[150:153], off offset:16 sc1

.LBB0_567:
	s_or_b64 exec, exec, s[8:9]
	s_and_saveexec_b64 s[42:43], s[40:41]
	s_cbranch_execz .LBB0_573
	v_mov_b32_e32 v150, v160
	v_mov_b32_e32 v151, v160
	v_pk_fma_f32 v[148:149], v[30:31], v[150:151], v[136:137]
	v_pk_fma_f32 v[146:147], v[28:29], v[160:161], v[134:135]
	v_pk_fma_f32 v[152:153], v[26:27], v[150:151], v[132:133]
	v_pk_fma_f32 v[150:151], v[24:25], v[160:161], v[130:131]
	v_cmp_le_i32_e32 vcc, s21, v162
	s_and_saveexec_b64 s[8:9], vcc
	s_xor_b64 s[8:9], exec, s[8:9]
	s_cbranch_execz .LBB0_571
	s_andn2_b64 vcc, exec, s[68:69]
	s_cbranch_vccnz .LBB0_571
	v_lshl_add_u64 v[156:157], s[46:47], 0, v[158:159]
	v_subrev_u32_e32 v48, s21, v162
	v_lshl_add_u64 v[156:157], v[48:49], 2, v[156:157]
	global_store_dwordx4 v[156:157], v[146:149], off sc1
	global_store_dwordx4 v[156:157], v[150:153], off offset:16 sc1

.LBB0_573:
	s_or_b64 exec, exec, s[42:43]
	v_fmamk_f32 v48, v165, 0x3a800000, v234
	v_mul_f32_e32 v146, 0x4b800000, v48
	v_cmp_gt_f32_e32 vcc, s27, v48
	v_add_u32_e32 v156, 0x90, v218
	v_ashrrev_i32_e32 v157, 31, v156
	v_cndmask_b32_e32 v48, v48, v146, vcc
	v_rsq_f32_e32 v48, v48
	v_lshlrev_b64 v[158:159], 7, v[156:157]
	v_mul_f32_e32 v146, 0x45800000, v48
	v_cndmask_b32_e32 v160, v48, v146, vcc
	v_mov_b32_e32 v161, v160
	s_and_saveexec_b64 s[8:9], s[0:1]
	s_cbranch_execz .LBB0_579
	v_mov_b32_e32 v150, v160
	v_mov_b32_e32 v151, v160
	v_pk_fma_f32 v[148:149], v[56:57], v[150:151], v[144:145]
	v_pk_fma_f32 v[146:147], v[54:55], v[160:161], v[142:143]
	v_pk_fma_f32 v[152:153], v[52:53], v[150:151], v[140:141]
	v_pk_fma_f32 v[150:151], v[50:51], v[160:161], v[138:139]
	v_cmp_le_i32_e32 vcc, s21, v154
	s_and_saveexec_b64 s[10:11], vcc
	s_xor_b64 s[10:11], exec, s[10:11]
	s_cbranch_execz .LBB0_577
	s_andn2_b64 vcc, exec, s[68:69]
	s_cbranch_vccnz .LBB0_577
	v_lshl_add_u64 v[166:167], s[46:47], 0, v[158:159]
	v_subrev_u32_e32 v48, s21, v154
	v_lshl_add_u64 v[166:167], v[48:49], 2, v[166:167]
	global_store_dwordx4 v[166:167], v[146:149], off sc1
	global_store_dwordx4 v[166:167], v[150:153], off offset:16 sc1

.LBB0_579:
	s_or_b64 exec, exec, s[8:9]
	s_and_saveexec_b64 s[42:43], s[40:41]
	s_cbranch_execz .LBB0_585
	v_mov_b32_e32 v150, v160
	v_mov_b32_e32 v151, v160
	v_pk_fma_f32 v[148:149], v[22:23], v[150:151], v[136:137]
	v_pk_fma_f32 v[146:147], v[20:21], v[160:161], v[134:135]
	v_pk_fma_f32 v[152:153], v[18:19], v[150:151], v[132:133]
	v_pk_fma_f32 v[150:151], v[16:17], v[160:161], v[130:131]
	v_cmp_le_i32_e32 vcc, s21, v162
	s_and_saveexec_b64 s[8:9], vcc
	s_xor_b64 s[8:9], exec, s[8:9]
	s_cbranch_execz .LBB0_583
	s_andn2_b64 vcc, exec, s[68:69]
	s_cbranch_vccnz .LBB0_583
	v_lshl_add_u64 v[156:157], s[46:47], 0, v[158:159]
	v_subrev_u32_e32 v48, s21, v162
	v_lshl_add_u64 v[156:157], v[48:49], 2, v[156:157]
	global_store_dwordx4 v[156:157], v[146:149], off sc1
	global_store_dwordx4 v[156:157], v[150:153], off offset:16 sc1

.LBB0_585:
	s_or_b64 exec, exec, s[42:43]
	v_fmamk_f32 v48, v164, 0x3a800000, v234
	v_mul_f32_e32 v146, 0x4b800000, v48
	v_cmp_gt_f32_e32 vcc, s27, v48
	v_add_u32_e32 v156, 0xa0, v218
	v_ashrrev_i32_e32 v157, 31, v156
	v_cndmask_b32_e32 v48, v48, v146, vcc
	v_rsq_f32_e32 v48, v48
	v_lshlrev_b64 v[158:159], 7, v[156:157]
	v_mul_f32_e32 v146, 0x45800000, v48
	v_cndmask_b32_e32 v160, v48, v146, vcc
	v_mov_b32_e32 v161, v160
	s_and_saveexec_b64 s[8:9], s[0:1]
	s_cbranch_execz .LBB0_591
	v_mov_b32_e32 v150, v160
	v_mov_b32_e32 v151, v160
	v_pk_fma_f32 v[148:149], v[46:47], v[150:151], v[144:145]
	v_pk_fma_f32 v[146:147], v[44:45], v[160:161], v[142:143]
	v_pk_fma_f32 v[152:153], v[42:43], v[150:151], v[140:141]
	v_pk_fma_f32 v[150:151], v[40:41], v[160:161], v[138:139]
	v_cmp_le_i32_e32 vcc, s21, v154
	s_and_saveexec_b64 s[10:11], vcc
	s_xor_b64 s[10:11], exec, s[10:11]
	s_cbranch_execz .LBB0_589
	s_andn2_b64 vcc, exec, s[68:69]
	s_cbranch_vccnz .LBB0_589
	v_lshl_add_u64 v[164:165], s[46:47], 0, v[158:159]
	v_subrev_u32_e32 v48, s21, v154
	v_lshl_add_u64 v[164:165], v[48:49], 2, v[164:165]
	global_store_dwordx4 v[164:165], v[146:149], off sc1
	global_store_dwordx4 v[164:165], v[150:153], off offset:16 sc1

.LBB0_591:
	s_or_b64 exec, exec, s[8:9]
	s_and_saveexec_b64 s[42:43], s[40:41]
	s_cbranch_execz .LBB0_597
	v_mov_b32_e32 v150, v160
	v_mov_b32_e32 v151, v160
	v_pk_fma_f32 v[148:149], v[14:15], v[150:151], v[136:137]
	v_pk_fma_f32 v[146:147], v[12:13], v[160:161], v[134:135]
	v_pk_fma_f32 v[152:153], v[10:11], v[150:151], v[132:133]
	v_pk_fma_f32 v[150:151], v[8:9], v[160:161], v[130:131]
	v_cmp_le_i32_e32 vcc, s21, v162
	s_and_saveexec_b64 s[8:9], vcc
	s_xor_b64 s[8:9], exec, s[8:9]
	s_cbranch_execz .LBB0_595
	s_andn2_b64 vcc, exec, s[68:69]
	s_cbranch_vccnz .LBB0_595
	v_lshl_add_u64 v[156:157], s[46:47], 0, v[158:159]
	v_subrev_u32_e32 v48, s21, v162
	v_lshl_add_u64 v[156:157], v[48:49], 2, v[156:157]
	global_store_dwordx4 v[156:157], v[146:149], off sc1
	global_store_dwordx4 v[156:157], v[150:153], off offset:16 sc1

.LBB0_597:
	s_or_b64 exec, exec, s[42:43]
	v_fmamk_f32 v48, v163, 0x3a800000, v234
	v_mul_f32_e32 v146, 0x4b800000, v48
	v_cmp_gt_f32_e32 vcc, s27, v48
	s_nop 1
	v_cndmask_b32_e32 v48, v48, v146, vcc
	v_rsq_f32_e32 v48, v48
	v_add_u32_e32 v146, 0xb0, v218
	v_ashrrev_i32_e32 v147, 31, v146
	v_mul_f32_e32 v148, 0x45800000, v48
	v_cndmask_b32_e32 v150, v48, v148, vcc
	v_mov_b32_e32 v151, v150
	v_lshlrev_b64 v[148:149], 7, v[146:147]
	s_and_saveexec_b64 s[8:9], s[0:1]
	s_cbranch_execz .LBB0_603
	v_mov_b32_e32 v152, v150
	v_mov_b32_e32 v153, v150
	v_pk_fma_f32 v[144:145], v[38:39], v[152:153], v[144:145]
	v_pk_fma_f32 v[142:143], v[36:37], v[150:151], v[142:143]
	v_pk_fma_f32 v[140:141], v[34:35], v[152:153], v[140:141]
	v_pk_fma_f32 v[138:139], v[32:33], v[150:151], v[138:139]
	v_cmp_le_i32_e32 vcc, s21, v154
	s_and_saveexec_b64 s[0:1], vcc
	s_xor_b64 s[0:1], exec, s[0:1]
	s_cbranch_execz .LBB0_601
	s_andn2_b64 vcc, exec, s[68:69]
	s_cbranch_vccnz .LBB0_601
	v_lshl_add_u64 v[152:153], s[46:47], 0, v[148:149]
	v_subrev_u32_e32 v48, s21, v154
	v_lshl_add_u64 v[152:153], v[48:49], 2, v[152:153]
	global_store_dwordx4 v[152:153], v[142:145], off sc1
	global_store_dwordx4 v[152:153], v[138:141], off offset:16 sc1
.LBB0_601:
	s_andn2_saveexec_b64 s[0:1], s[0:1]
	s_cbranch_execz .LBB0_603
	v_cvt_pk_bf16_f32 v142, v142, v143
	v_cvt_pk_bf16_f32 v143, v144, v145
	v_cvt_pk_bf16_f32 v144, v138, v139
	v_mad_i64_i32 v[138:139], s[0:1], v146, s21, 0
	v_lshl_add_u64 v[138:139], v[138:139], 1, s[4:5]
	v_ashrrev_i32_e32 v155, 31, v154
	v_lshl_add_u64 v[138:139], v[154:155], 1, v[138:139]
	v_cvt_pk_bf16_f32 v145, v140, v141
	global_store_dwordx4 v[138:139], v[142:145], off sc1
.LBB0_603:
	s_or_b64 exec, exec, s[8:9]
	s_and_saveexec_b64 s[0:1], s[40:41]
	s_cbranch_execz .LBB0_609
	v_mov_b32_e32 v138, v150
	v_mov_b32_e32 v139, v150
	v_pk_fma_f32 v[136:137], v[6:7], v[138:139], v[136:137]
	v_pk_fma_f32 v[134:135], v[4:5], v[150:151], v[134:135]
	v_pk_fma_f32 v[132:133], v[2:3], v[138:139], v[132:133]
	v_pk_fma_f32 v[130:131], v[0:1], v[150:151], v[130:131]
	v_cmp_le_i32_e32 vcc, s21, v162
	s_and_saveexec_b64 s[8:9], vcc
	s_xor_b64 s[8:9], exec, s[8:9]
	s_cbranch_execz .LBB0_607
	s_andn2_b64 vcc, exec, s[68:69]
	s_cbranch_vccnz .LBB0_607
	v_lshl_add_u64 v[138:139], s[46:47], 0, v[148:149]
	v_subrev_u32_e32 v48, s21, v162
	v_lshl_add_u64 v[138:139], v[48:49], 2, v[138:139]
	global_store_dwordx4 v[138:139], v[134:137], off sc1
	global_store_dwordx4 v[138:139], v[130:133], off offset:16 sc1
.LBB0_607:
	s_andn2_saveexec_b64 s[8:9], s[8:9]
	s_cbranch_execz .LBB0_609
	v_cvt_pk_bf16_f32 v134, v134, v135
	v_cvt_pk_bf16_f32 v135, v136, v137
	v_cvt_pk_bf16_f32 v136, v130, v131
	v_mad_i64_i32 v[130:131], s[8:9], v146, s21, 0
	v_lshl_add_u64 v[130:131], v[130:131], 1, s[4:5]
	v_ashrrev_i32_e32 v155, 31, v154
	v_lshl_add_u64 v[130:131], v[154:155], 1, v[130:131]
	v_cvt_pk_bf16_f32 v137, v132, v133
	global_store_dwordx4 v[130:131], v[134:137], off offset:256 sc1

.Lpl_wdone_2:
.Lpl_loop_6:
	s_add_i32 s0, s40, 1
	s_min_i32 s0, s0, s41
	v_cvt_f32_u32_e32 v98, s0
	v_div_scale_f32 v99, s[10:11], v98, v98, 1.0
	v_rcp_f32_e32 v100, v99
	s_nop 0
	v_fma_f32 v101, -v99, v100, 1.0
	v_fmac_f32_e32 v100, v101, v100
	v_div_scale_f32 v101, vcc, 1.0, v98, 1.0
	v_mul_f32_e32 v102, v101, v100
	v_fma_f32 v103, -v99, v102, v101
	v_fmac_f32_e32 v102, v103, v100
	v_fma_f32 v99, -v99, v102, v101
	v_div_fmas_f32 v99, v99, v100, v102
	v_div_fixup_f32 v94, v99, v98, 1.0
	v_mov_b32_e32 v95, v94
	v_lshlrev_b32_e32 v40, 16, v0
	v_and_b32_e32 v41, 0xffff0000, v0
	v_lshlrev_b32_e32 v42, 16, v1
	v_and_b32_e32 v43, 0xffff0000, v1
	v_lshlrev_b32_e32 v44, 16, v2
	v_and_b32_e32 v45, 0xffff0000, v2
	v_lshlrev_b32_e32 v46, 16, v3
	v_and_b32_e32 v47, 0xffff0000, v3
	v_pk_add_f32 v[32:33], v[32:33], v[40:41]
	v_pk_add_f32 v[34:35], v[34:35], v[42:43]
	v_pk_add_f32 v[36:37], v[36:37], v[44:45]
	v_pk_add_f32 v[38:39], v[38:39], v[46:47]
	v_pk_fma_f32 v[82:83], v[32:33], v[94:95], v[40:41] neg_lo:[0,0,1] neg_hi:[0,0,1]
	v_pk_fma_f32 v[84:85], v[34:35], v[94:95], v[42:43] neg_lo:[0,0,1] neg_hi:[0,0,1]
	v_pk_fma_f32 v[86:87], v[36:37], v[94:95], v[44:45] neg_lo:[0,0,1] neg_hi:[0,0,1]
	v_pk_fma_f32 v[88:89], v[38:39], v[94:95], v[46:47] neg_lo:[0,0,1] neg_hi:[0,0,1]
	v_cvt_pk_bf16_f32 v90, v82, v83
	v_cvt_pk_bf16_f32 v91, v84, v85
	v_cvt_pk_bf16_f32 v92, v86, v87
	v_cvt_pk_bf16_f32 v93, v88, v89
	global_store_dwordx4 v48, v[90:93], s[22:23] sc1
	s_add_u32 s22, s22, 0x1000
	s_addc_u32 s23, s23, 0
	s_add_i32 s0, s40, 0
	s_cmp_lt_i32 s0, s43
	s_cbranch_scc1 .Lpl_sk_7
	v_lshlrev_b32_e32 v82, 16, v16
	v_and_b32_e32 v83, 0xffff0000, v16
	v_lshlrev_b32_e32 v84, 16, v17
	v_and_b32_e32 v85, 0xffff0000, v17
	v_lshlrev_b32_e32 v86, 16, v18
	v_and_b32_e32 v87, 0xffff0000, v18
	v_lshlrev_b32_e32 v88, 16, v19
	v_and_b32_e32 v89, 0xffff0000, v19
	v_pk_add_f32 v[32:33], v[32:33], v[82:83] neg_lo:[0,1] neg_hi:[0,1]
	v_pk_add_f32 v[34:35], v[34:35], v[84:85] neg_lo:[0,1] neg_hi:[0,1]
	v_pk_add_f32 v[36:37], v[36:37], v[86:87] neg_lo:[0,1] neg_hi:[0,1]
	v_pk_add_f32 v[38:39], v[38:39], v[88:89] neg_lo:[0,1] neg_hi:[0,1]
.Lpl_sk_7:
	s_add_i32 s0, s40, 2
	s_min_i32 s0, s0, s41
	v_cvt_f32_u32_e32 v98, s0
	v_div_scale_f32 v99, s[10:11], v98, v98, 1.0
	v_rcp_f32_e32 v100, v99
	s_nop 0
	v_fma_f32 v101, -v99, v100, 1.0
	v_fmac_f32_e32 v100, v101, v100
	v_div_scale_f32 v101, vcc, 1.0, v98, 1.0
	v_mul_f32_e32 v102, v101, v100
	v_fma_f32 v103, -v99, v102, v101
	v_fmac_f32_e32 v102, v103, v100
	v_fma_f32 v99, -v99, v102, v101
	v_div_fmas_f32 v99, v99, v100, v102
	v_div_fixup_f32 v94, v99, v98, 1.0
	v_mov_b32_e32 v95, v94
	v_lshlrev_b32_e32 v40, 16, v4
	v_and_b32_e32 v41, 0xffff0000, v4
	v_lshlrev_b32_e32 v42, 16, v5
	v_and_b32_e32 v43, 0xffff0000, v5
	v_lshlrev_b32_e32 v44, 16, v6
	v_and_b32_e32 v45, 0xffff0000, v6
	v_lshlrev_b32_e32 v46, 16, v7
	v_and_b32_e32 v47, 0xffff0000, v7
	v_pk_add_f32 v[32:33], v[32:33], v[40:41]
	v_pk_add_f32 v[34:35], v[34:35], v[42:43]
	v_pk_add_f32 v[36:37], v[36:37], v[44:45]
	v_pk_add_f32 v[38:39], v[38:39], v[46:47]
	v_pk_fma_f32 v[82:83], v[32:33], v[94:95], v[40:41] neg_lo:[0,0,1] neg_hi:[0,0,1]
	v_pk_fma_f32 v[84:85], v[34:35], v[94:95], v[42:43] neg_lo:[0,0,1] neg_hi:[0,0,1]
	v_pk_fma_f32 v[86:87], v[36:37], v[94:95], v[44:45] neg_lo:[0,0,1] neg_hi:[0,0,1]
	v_pk_fma_f32 v[88:89], v[38:39], v[94:95], v[46:47] neg_lo:[0,0,1] neg_hi:[0,0,1]
	v_cvt_pk_bf16_f32 v90, v82, v83
	v_cvt_pk_bf16_f32 v91, v84, v85
	v_cvt_pk_bf16_f32 v92, v86, v87
	v_cvt_pk_bf16_f32 v93, v88, v89
	global_store_dwordx4 v48, v[90:93], s[22:23] sc1
	s_add_u32 s22, s22, 0x1000
	s_addc_u32 s23, s23, 0
	s_add_i32 s0, s40, 1
	s_cmp_lt_i32 s0, s43
	s_cbranch_scc1 .Lpl_sk_8
	v_lshlrev_b32_e32 v82, 16, v20
	v_and_b32_e32 v83, 0xffff0000, v20
	v_lshlrev_b32_e32 v84, 16, v21
	v_and_b32_e32 v85, 0xffff0000, v21
	v_lshlrev_b32_e32 v86, 16, v22
	v_and_b32_e32 v87, 0xffff0000, v22
	v_lshlrev_b32_e32 v88, 16, v23
	v_and_b32_e32 v89, 0xffff0000, v23
	v_pk_add_f32 v[32:33], v[32:33], v[82:83] neg_lo:[0,1] neg_hi:[0,1]
	v_pk_add_f32 v[34:35], v[34:35], v[84:85] neg_lo:[0,1] neg_hi:[0,1]
	v_pk_add_f32 v[36:37], v[36:37], v[86:87] neg_lo:[0,1] neg_hi:[0,1]
	v_pk_add_f32 v[38:39], v[38:39], v[88:89] neg_lo:[0,1] neg_hi:[0,1]
.Lpl_sk_8:
	s_add_i32 s0, s40, 3
	s_min_i32 s0, s0, s41
	v_cvt_f32_u32_e32 v98, s0
	v_div_scale_f32 v99, s[10:11], v98, v98, 1.0
	v_rcp_f32_e32 v100, v99
	s_nop 0
	v_fma_f32 v101, -v99, v100, 1.0
	v_fmac_f32_e32 v100, v101, v100
	v_div_scale_f32 v101, vcc, 1.0, v98, 1.0
	v_mul_f32_e32 v102, v101, v100
	v_fma_f32 v103, -v99, v102, v101
	v_fmac_f32_e32 v102, v103, v100
	v_fma_f32 v99, -v99, v102, v101
	v_div_fmas_f32 v99, v99, v100, v102
	v_div_fixup_f32 v94, v99, v98, 1.0
	v_mov_b32_e32 v95, v94
	v_lshlrev_b32_e32 v40, 16, v8
	v_and_b32_e32 v41, 0xffff0000, v8
	v_lshlrev_b32_e32 v42, 16, v9
	v_and_b32_e32 v43, 0xffff0000, v9
	v_lshlrev_b32_e32 v44, 16, v10
	v_and_b32_e32 v45, 0xffff0000, v10
	v_lshlrev_b32_e32 v46, 16, v11
	v_and_b32_e32 v47, 0xffff0000, v11
	v_pk_add_f32 v[32:33], v[32:33], v[40:41]
	v_pk_add_f32 v[34:35], v[34:35], v[42:43]
	v_pk_add_f32 v[36:37], v[36:37], v[44:45]
	v_pk_add_f32 v[38:39], v[38:39], v[46:47]
	v_pk_fma_f32 v[82:83], v[32:33], v[94:95], v[40:41] neg_lo:[0,0,1] neg_hi:[0,0,1]
	v_pk_fma_f32 v[84:85], v[34:35], v[94:95], v[42:43] neg_lo:[0,0,1] neg_hi:[0,0,1]
	v_pk_fma_f32 v[86:87], v[36:37], v[94:95], v[44:45] neg_lo:[0,0,1] neg_hi:[0,0,1]
	v_pk_fma_f32 v[88:89], v[38:39], v[94:95], v[46:47] neg_lo:[0,0,1] neg_hi:[0,0,1]
	v_cvt_pk_bf16_f32 v90, v82, v83
	v_cvt_pk_bf16_f32 v91, v84, v85
	v_cvt_pk_bf16_f32 v92, v86, v87
	v_cvt_pk_bf16_f32 v93, v88, v89
	global_store_dwordx4 v48, v[90:93], s[22:23] sc1
	s_add_u32 s22, s22, 0x1000
	s_addc_u32 s23, s23, 0
	s_add_i32 s0, s40, 2
	s_cmp_lt_i32 s0, s43
	s_cbranch_scc1 .Lpl_sk_9
	v_lshlrev_b32_e32 v82, 16, v24
	v_and_b32_e32 v83, 0xffff0000, v24
	v_lshlrev_b32_e32 v84, 16, v25
	v_and_b32_e32 v85, 0xffff0000, v25
	v_lshlrev_b32_e32 v86, 16, v26
	v_and_b32_e32 v87, 0xffff0000, v26
	v_lshlrev_b32_e32 v88, 16, v27
	v_and_b32_e32 v89, 0xffff0000, v27
	v_pk_add_f32 v[32:33], v[32:33], v[82:83] neg_lo:[0,1] neg_hi:[0,1]
	v_pk_add_f32 v[34:35], v[34:35], v[84:85] neg_lo:[0,1] neg_hi:[0,1]
	v_pk_add_f32 v[36:37], v[36:37], v[86:87] neg_lo:[0,1] neg_hi:[0,1]
	v_pk_add_f32 v[38:39], v[38:39], v[88:89] neg_lo:[0,1] neg_hi:[0,1]
.Lpl_sk_9:
	s_add_i32 s0, s40, 4
	s_min_i32 s0, s0, s41
	v_cvt_f32_u32_e32 v98, s0
	v_div_scale_f32 v99, s[10:11], v98, v98, 1.0
	v_rcp_f32_e32 v100, v99
	s_nop 0
	v_fma_f32 v101, -v99, v100, 1.0
	v_fmac_f32_e32 v100, v101, v100
	v_div_scale_f32 v101, vcc, 1.0, v98, 1.0
	v_mul_f32_e32 v102, v101, v100
	v_fma_f32 v103, -v99, v102, v101
	v_fmac_f32_e32 v102, v103, v100
	v_fma_f32 v99, -v99, v102, v101
	v_div_fmas_f32 v99, v99, v100, v102
	v_div_fixup_f32 v94, v99, v98, 1.0
	v_mov_b32_e32 v95, v94
	v_lshlrev_b32_e32 v40, 16, v12
	v_and_b32_e32 v41, 0xffff0000, v12
	v_lshlrev_b32_e32 v42, 16, v13
	v_and_b32_e32 v43, 0xffff0000, v13
	v_lshlrev_b32_e32 v44, 16, v14
	v_and_b32_e32 v45, 0xffff0000, v14
	v_lshlrev_b32_e32 v46, 16, v15
	v_and_b32_e32 v47, 0xffff0000, v15
	v_pk_add_f32 v[32:33], v[32:33], v[40:41]
	v_pk_add_f32 v[34:35], v[34:35], v[42:43]
	v_pk_add_f32 v[36:37], v[36:37], v[44:45]
	v_pk_add_f32 v[38:39], v[38:39], v[46:47]
	v_pk_fma_f32 v[82:83], v[32:33], v[94:95], v[40:41] neg_lo:[0,0,1] neg_hi:[0,0,1]
	v_pk_fma_f32 v[84:85], v[34:35], v[94:95], v[42:43] neg_lo:[0,0,1] neg_hi:[0,0,1]
	v_pk_fma_f32 v[86:87], v[36:37], v[94:95], v[44:45] neg_lo:[0,0,1] neg_hi:[0,0,1]
	v_pk_fma_f32 v[88:89], v[38:39], v[94:95], v[46:47] neg_lo:[0,0,1] neg_hi:[0,0,1]
	v_cvt_pk_bf16_f32 v90, v82, v83
	v_cvt_pk_bf16_f32 v91, v84, v85
	v_cvt_pk_bf16_f32 v92, v86, v87
	v_cvt_pk_bf16_f32 v93, v88, v89
	global_store_dwordx4 v48, v[90:93], s[22:23] sc1
	s_add_u32 s22, s22, 0x1000
	s_addc_u32 s23, s23, 0
	s_add_i32 s0, s40, 3
	s_cmp_lt_i32 s0, s43
	s_cbranch_scc1 .Lpl_sk_10
	v_lshlrev_b32_e32 v82, 16, v28
	v_and_b32_e32 v83, 0xffff0000, v28
	v_lshlrev_b32_e32 v84, 16, v29
	v_and_b32_e32 v85, 0xffff0000, v29
	v_lshlrev_b32_e32 v86, 16, v30
	v_and_b32_e32 v87, 0xffff0000, v30
	v_lshlrev_b32_e32 v88, 16, v31
	v_and_b32_e32 v89, 0xffff0000, v31
	v_pk_add_f32 v[32:33], v[32:33], v[82:83] neg_lo:[0,1] neg_hi:[0,1]
	v_pk_add_f32 v[34:35], v[34:35], v[84:85] neg_lo:[0,1] neg_hi:[0,1]
	v_pk_add_f32 v[36:37], v[36:37], v[86:87] neg_lo:[0,1] neg_hi:[0,1]
	v_pk_add_f32 v[38:39], v[38:39], v[88:89] neg_lo:[0,1] neg_hi:[0,1]
.Lpl_sk_10:
	s_add_i32 s46, s40, 8
	s_add_i32 s0, s48, -4
	s_min_i32 s46, s46, s0
	s_add_i32 s0, s42, s46
	s_lshl_b32 s0, s0, 13
	s_add_u32 s8, s4, s0
	s_addc_u32 s9, s5, 0
	global_load_dwordx4 v[0:3], v48, s[8:9]
	s_add_u32 s8, s8, 0x2000
	s_addc_u32 s9, s9, 0
	global_load_dwordx4 v[4:7], v48, s[8:9]
	s_add_u32 s8, s8, 0x2000
	s_addc_u32 s9, s9, 0
	global_load_dwordx4 v[8:11], v48, s[8:9]
	s_add_u32 s8, s8, 0x2000
	s_addc_u32 s9, s9, 0
	global_load_dwordx4 v[12:15], v48, s[8:9]
	s_sub_i32 s1, s46, s43
	s_add_i32 s0, s1, 0
	s_max_i32 s0, s0, 0
	s_add_i32 s0, s0, s42
	s_lshl_b32 s0, s0, 13
	s_add_u32 s10, s4, s0
	s_addc_u32 s11, s5, 0
	global_load_dwordx4 v[16:19], v48, s[10:11]
	s_add_i32 s0, s1, 1
	s_max_i32 s0, s0, 0
	s_add_i32 s0, s0, s42
	s_lshl_b32 s0, s0, 13
	s_add_u32 s10, s4, s0
	s_addc_u32 s11, s5, 0
	global_load_dwordx4 v[20:23], v48, s[10:11]
	s_add_i32 s0, s1, 2
	s_max_i32 s0, s0, 0
	s_add_i32 s0, s0, s42
	s_lshl_b32 s0, s0, 13
	s_add_u32 s10, s4, s0
	s_addc_u32 s11, s5, 0
	global_load_dwordx4 v[24:27], v48, s[10:11]
	s_add_i32 s0, s1, 3
	s_max_i32 s0, s0, 0
	s_add_i32 s0, s0, s42
	s_lshl_b32 s0, s0, 13
	s_add_u32 s10, s4, s0
	s_addc_u32 s11, s5, 0
	global_load_dwordx4 v[28:31], v48, s[10:11]
	s_waitcnt vmcnt(12)
	s_add_i32 s47, s40, 4
	s_add_i32 s0, s47, 1
	s_min_i32 s0, s0, s41
	v_cvt_f32_u32_e32 v98, s0
	v_div_scale_f32 v99, s[10:11], v98, v98, 1.0
	v_rcp_f32_e32 v100, v99
	s_nop 0
	v_fma_f32 v101, -v99, v100, 1.0
	v_fmac_f32_e32 v100, v101, v100
	v_div_scale_f32 v101, vcc, 1.0, v98, 1.0
	v_mul_f32_e32 v102, v101, v100
	v_fma_f32 v103, -v99, v102, v101
	v_fmac_f32_e32 v102, v103, v100
	v_fma_f32 v99, -v99, v102, v101
	v_div_fmas_f32 v99, v99, v100, v102
	v_div_fixup_f32 v94, v99, v98, 1.0
	v_mov_b32_e32 v95, v94
	v_lshlrev_b32_e32 v40, 16, v50
	v_and_b32_e32 v41, 0xffff0000, v50
	v_lshlrev_b32_e32 v42, 16, v51
	v_and_b32_e32 v43, 0xffff0000, v51
	v_lshlrev_b32_e32 v44, 16, v52
	v_and_b32_e32 v45, 0xffff0000, v52
	v_lshlrev_b32_e32 v46, 16, v53
	v_and_b32_e32 v47, 0xffff0000, v53
	v_pk_add_f32 v[32:33], v[32:33], v[40:41]
	v_pk_add_f32 v[34:35], v[34:35], v[42:43]
	v_pk_add_f32 v[36:37], v[36:37], v[44:45]
	v_pk_add_f32 v[38:39], v[38:39], v[46:47]
	v_pk_fma_f32 v[82:83], v[32:33], v[94:95], v[40:41] neg_lo:[0,0,1] neg_hi:[0,0,1]
	v_pk_fma_f32 v[84:85], v[34:35], v[94:95], v[42:43] neg_lo:[0,0,1] neg_hi:[0,0,1]
	v_pk_fma_f32 v[86:87], v[36:37], v[94:95], v[44:45] neg_lo:[0,0,1] neg_hi:[0,0,1]
	v_pk_fma_f32 v[88:89], v[38:39], v[94:95], v[46:47] neg_lo:[0,0,1] neg_hi:[0,0,1]
	v_cvt_pk_bf16_f32 v90, v82, v83
	v_cvt_pk_bf16_f32 v91, v84, v85
	v_cvt_pk_bf16_f32 v92, v86, v87
	v_cvt_pk_bf16_f32 v93, v88, v89
	global_store_dwordx4 v48, v[90:93], s[22:23] sc1
	s_add_u32 s22, s22, 0x1000
	s_addc_u32 s23, s23, 0
	s_add_i32 s0, s47, 0
	s_cmp_lt_i32 s0, s43
	s_cbranch_scc1 .Lpl_sk_11
	v_lshlrev_b32_e32 v82, 16, v66
	v_and_b32_e32 v83, 0xffff0000, v66
	v_lshlrev_b32_e32 v84, 16, v67
	v_and_b32_e32 v85, 0xffff0000, v67
	v_lshlrev_b32_e32 v86, 16, v68
	v_and_b32_e32 v87, 0xffff0000, v68
	v_lshlrev_b32_e32 v88, 16, v69
	v_and_b32_e32 v89, 0xffff0000, v69
	v_pk_add_f32 v[32:33], v[32:33], v[82:83] neg_lo:[0,1] neg_hi:[0,1]
	v_pk_add_f32 v[34:35], v[34:35], v[84:85] neg_lo:[0,1] neg_hi:[0,1]
	v_pk_add_f32 v[36:37], v[36:37], v[86:87] neg_lo:[0,1] neg_hi:[0,1]
	v_pk_add_f32 v[38:39], v[38:39], v[88:89] neg_lo:[0,1] neg_hi:[0,1]
.Lpl_sk_11:
	s_add_i32 s0, s47, 2
	s_min_i32 s0, s0, s41
	v_cvt_f32_u32_e32 v98, s0
	v_div_scale_f32 v99, s[10:11], v98, v98, 1.0
	v_rcp_f32_e32 v100, v99
	s_nop 0
	v_fma_f32 v101, -v99, v100, 1.0
	v_fmac_f32_e32 v100, v101, v100
	v_div_scale_f32 v101, vcc, 1.0, v98, 1.0
	v_mul_f32_e32 v102, v101, v100
	v_fma_f32 v103, -v99, v102, v101
	v_fmac_f32_e32 v102, v103, v100
	v_fma_f32 v99, -v99, v102, v101
	v_div_fmas_f32 v99, v99, v100, v102
	v_div_fixup_f32 v94, v99, v98, 1.0
	v_mov_b32_e32 v95, v94
	v_lshlrev_b32_e32 v40, 16, v54
	v_and_b32_e32 v41, 0xffff0000, v54
	v_lshlrev_b32_e32 v42, 16, v55
	v_and_b32_e32 v43, 0xffff0000, v55
	v_lshlrev_b32_e32 v44, 16, v56
	v_and_b32_e32 v45, 0xffff0000, v56
	v_lshlrev_b32_e32 v46, 16, v57
	v_and_b32_e32 v47, 0xffff0000, v57
	v_pk_add_f32 v[32:33], v[32:33], v[40:41]
	v_pk_add_f32 v[34:35], v[34:35], v[42:43]
	v_pk_add_f32 v[36:37], v[36:37], v[44:45]
	v_pk_add_f32 v[38:39], v[38:39], v[46:47]
	v_pk_fma_f32 v[82:83], v[32:33], v[94:95], v[40:41] neg_lo:[0,0,1] neg_hi:[0,0,1]
	v_pk_fma_f32 v[84:85], v[34:35], v[94:95], v[42:43] neg_lo:[0,0,1] neg_hi:[0,0,1]
	v_pk_fma_f32 v[86:87], v[36:37], v[94:95], v[44:45] neg_lo:[0,0,1] neg_hi:[0,0,1]
	v_pk_fma_f32 v[88:89], v[38:39], v[94:95], v[46:47] neg_lo:[0,0,1] neg_hi:[0,0,1]
	v_cvt_pk_bf16_f32 v90, v82, v83
	v_cvt_pk_bf16_f32 v91, v84, v85
	v_cvt_pk_bf16_f32 v92, v86, v87
	v_cvt_pk_bf16_f32 v93, v88, v89
	global_store_dwordx4 v48, v[90:93], s[22:23] sc1
	s_add_u32 s22, s22, 0x1000
	s_addc_u32 s23, s23, 0
	s_add_i32 s0, s47, 1
	s_cmp_lt_i32 s0, s43
	s_cbranch_scc1 .Lpl_sk_12
	v_lshlrev_b32_e32 v82, 16, v70
	v_and_b32_e32 v83, 0xffff0000, v70
	v_lshlrev_b32_e32 v84, 16, v71
	v_and_b32_e32 v85, 0xffff0000, v71
	v_lshlrev_b32_e32 v86, 16, v72
	v_and_b32_e32 v87, 0xffff0000, v72
	v_lshlrev_b32_e32 v88, 16, v73
	v_and_b32_e32 v89, 0xffff0000, v73
	v_pk_add_f32 v[32:33], v[32:33], v[82:83] neg_lo:[0,1] neg_hi:[0,1]
	v_pk_add_f32 v[34:35], v[34:35], v[84:85] neg_lo:[0,1] neg_hi:[0,1]
	v_pk_add_f32 v[36:37], v[36:37], v[86:87] neg_lo:[0,1] neg_hi:[0,1]
	v_pk_add_f32 v[38:39], v[38:39], v[88:89] neg_lo:[0,1] neg_hi:[0,1]
.Lpl_sk_12:
	s_add_i32 s0, s47, 3
	s_min_i32 s0, s0, s41
	v_cvt_f32_u32_e32 v98, s0
	v_div_scale_f32 v99, s[10:11], v98, v98, 1.0
	v_rcp_f32_e32 v100, v99
	s_nop 0
	v_fma_f32 v101, -v99, v100, 1.0
	v_fmac_f32_e32 v100, v101, v100
	v_div_scale_f32 v101, vcc, 1.0, v98, 1.0
	v_mul_f32_e32 v102, v101, v100
	v_fma_f32 v103, -v99, v102, v101
	v_fmac_f32_e32 v102, v103, v100
	v_fma_f32 v99, -v99, v102, v101
	v_div_fmas_f32 v99, v99, v100, v102
	v_div_fixup_f32 v94, v99, v98, 1.0
	v_mov_b32_e32 v95, v94
	v_lshlrev_b32_e32 v40, 16, v58
	v_and_b32_e32 v41, 0xffff0000, v58
	v_lshlrev_b32_e32 v42, 16, v59
	v_and_b32_e32 v43, 0xffff0000, v59
	v_lshlrev_b32_e32 v44, 16, v60
	v_and_b32_e32 v45, 0xffff0000, v60
	v_lshlrev_b32_e32 v46, 16, v61
	v_and_b32_e32 v47, 0xffff0000, v61
	v_pk_add_f32 v[32:33], v[32:33], v[40:41]
	v_pk_add_f32 v[34:35], v[34:35], v[42:43]
	v_pk_add_f32 v[36:37], v[36:37], v[44:45]
	v_pk_add_f32 v[38:39], v[38:39], v[46:47]
	v_pk_fma_f32 v[82:83], v[32:33], v[94:95], v[40:41] neg_lo:[0,0,1] neg_hi:[0,0,1]
	v_pk_fma_f32 v[84:85], v[34:35], v[94:95], v[42:43] neg_lo:[0,0,1] neg_hi:[0,0,1]
	v_pk_fma_f32 v[86:87], v[36:37], v[94:95], v[44:45] neg_lo:[0,0,1] neg_hi:[0,0,1]
	v_pk_fma_f32 v[88:89], v[38:39], v[94:95], v[46:47] neg_lo:[0,0,1] neg_hi:[0,0,1]
	v_cvt_pk_bf16_f32 v90, v82, v83
	v_cvt_pk_bf16_f32 v91, v84, v85
	v_cvt_pk_bf16_f32 v92, v86, v87
	v_cvt_pk_bf16_f32 v93, v88, v89
	global_store_dwordx4 v48, v[90:93], s[22:23] sc1
	s_add_u32 s22, s22, 0x1000
	s_addc_u32 s23, s23, 0
	s_add_i32 s0, s47, 2
	s_cmp_lt_i32 s0, s43
	s_cbranch_scc1 .Lpl_sk_13
	v_lshlrev_b32_e32 v82, 16, v74
	v_and_b32_e32 v83, 0xffff0000, v74
	v_lshlrev_b32_e32 v84, 16, v75
	v_and_b32_e32 v85, 0xffff0000, v75
	v_lshlrev_b32_e32 v86, 16, v76
	v_and_b32_e32 v87, 0xffff0000, v76
	v_lshlrev_b32_e32 v88, 16, v77
	v_and_b32_e32 v89, 0xffff0000, v77
	v_pk_add_f32 v[32:33], v[32:33], v[82:83] neg_lo:[0,1] neg_hi:[0,1]
	v_pk_add_f32 v[34:35], v[34:35], v[84:85] neg_lo:[0,1] neg_hi:[0,1]
	v_pk_add_f32 v[36:37], v[36:37], v[86:87] neg_lo:[0,1] neg_hi:[0,1]
	v_pk_add_f32 v[38:39], v[38:39], v[88:89] neg_lo:[0,1] neg_hi:[0,1]
.Lpl_sk_13:
	s_add_i32 s0, s47, 4
	s_min_i32 s0, s0, s41
	v_cvt_f32_u32_e32 v98, s0
	v_div_scale_f32 v99, s[10:11], v98, v98, 1.0
	v_rcp_f32_e32 v100, v99
	s_nop 0
	v_fma_f32 v101, -v99, v100, 1.0
	v_fmac_f32_e32 v100, v101, v100
	v_div_scale_f32 v101, vcc, 1.0, v98, 1.0
	v_mul_f32_e32 v102, v101, v100
	v_fma_f32 v103, -v99, v102, v101
	v_fmac_f32_e32 v102, v103, v100
	v_fma_f32 v99, -v99, v102, v101
	v_div_fmas_f32 v99, v99, v100, v102
	v_div_fixup_f32 v94, v99, v98, 1.0
	v_mov_b32_e32 v95, v94
	v_lshlrev_b32_e32 v40, 16, v62
	v_and_b32_e32 v41, 0xffff0000, v62
	v_lshlrev_b32_e32 v42, 16, v63
	v_and_b32_e32 v43, 0xffff0000, v63
	v_lshlrev_b32_e32 v44, 16, v64
	v_and_b32_e32 v45, 0xffff0000, v64
	v_lshlrev_b32_e32 v46, 16, v65
	v_and_b32_e32 v47, 0xffff0000, v65
	v_pk_add_f32 v[32:33], v[32:33], v[40:41]
	v_pk_add_f32 v[34:35], v[34:35], v[42:43]
	v_pk_add_f32 v[36:37], v[36:37], v[44:45]
	v_pk_add_f32 v[38:39], v[38:39], v[46:47]
	v_pk_fma_f32 v[82:83], v[32:33], v[94:95], v[40:41] neg_lo:[0,0,1] neg_hi:[0,0,1]
	v_pk_fma_f32 v[84:85], v[34:35], v[94:95], v[42:43] neg_lo:[0,0,1] neg_hi:[0,0,1]
	v_pk_fma_f32 v[86:87], v[36:37], v[94:95], v[44:45] neg_lo:[0,0,1] neg_hi:[0,0,1]
	v_pk_fma_f32 v[88:89], v[38:39], v[94:95], v[46:47] neg_lo:[0,0,1] neg_hi:[0,0,1]
	v_cvt_pk_bf16_f32 v90, v82, v83
	v_cvt_pk_bf16_f32 v91, v84, v85
	v_cvt_pk_bf16_f32 v92, v86, v87
	v_cvt_pk_bf16_f32 v93, v88, v89
	global_store_dwordx4 v48, v[90:93], s[22:23] sc1
	s_add_u32 s22, s22, 0x1000
	s_addc_u32 s23, s23, 0
	s_add_i32 s0, s47, 3
	s_cmp_lt_i32 s0, s43
	s_cbranch_scc1 .Lpl_sk_14
	v_lshlrev_b32_e32 v82, 16, v78
	v_and_b32_e32 v83, 0xffff0000, v78
	v_lshlrev_b32_e32 v84, 16, v79
	v_and_b32_e32 v85, 0xffff0000, v79
	v_lshlrev_b32_e32 v86, 16, v80
	v_and_b32_e32 v87, 0xffff0000, v80
	v_lshlrev_b32_e32 v88, 16, v81
	v_and_b32_e32 v89, 0xffff0000, v81
	v_pk_add_f32 v[32:33], v[32:33], v[82:83] neg_lo:[0,1] neg_hi:[0,1]
	v_pk_add_f32 v[34:35], v[34:35], v[84:85] neg_lo:[0,1] neg_hi:[0,1]
	v_pk_add_f32 v[36:37], v[36:37], v[86:87] neg_lo:[0,1] neg_hi:[0,1]
	v_pk_add_f32 v[38:39], v[38:39], v[88:89] neg_lo:[0,1] neg_hi:[0,1]

.Lpl_oe_32:
	s_waitcnt vmcnt(0)
	v_lshlrev_b32_e32 v40, 16, v0
	v_and_b32_e32 v41, 0xffff0000, v0
	v_lshlrev_b32_e32 v42, 16, v1
	v_and_b32_e32 v43, 0xffff0000, v1
	v_lshlrev_b32_e32 v44, 16, v2
	v_and_b32_e32 v45, 0xffff0000, v2
	v_lshlrev_b32_e32 v46, 16, v3
	v_and_b32_e32 v47, 0xffff0000, v3
	v_pk_add_f32 v[32:33], v[32:33], v[40:41]
	v_pk_add_f32 v[34:35], v[34:35], v[42:43]
	v_pk_add_f32 v[36:37], v[36:37], v[44:45]
	v_pk_add_f32 v[38:39], v[38:39], v[46:47]
	v_pk_fma_f32 v[82:83], v[32:33], v[94:95], v[40:41] neg_lo:[0,0,1] neg_hi:[0,0,1]
	v_pk_fma_f32 v[84:85], v[34:35], v[94:95], v[42:43] neg_lo:[0,0,1] neg_hi:[0,0,1]
	v_pk_fma_f32 v[86:87], v[36:37], v[94:95], v[44:45] neg_lo:[0,0,1] neg_hi:[0,0,1]
	v_pk_fma_f32 v[88:89], v[38:39], v[94:95], v[46:47] neg_lo:[0,0,1] neg_hi:[0,0,1]
	v_cvt_pk_bf16_f32 v90, v82, v83
	v_cvt_pk_bf16_f32 v91, v84, v85
	v_cvt_pk_bf16_f32 v92, v86, v87
	v_cvt_pk_bf16_f32 v93, v88, v89
	global_store_dwordx4 v48, v[90:93], s[22:23] sc1
	s_add_u32 s22, s22, 0x1000
	s_addc_u32 s23, s23, 0
	s_cmp_lt_i32 s43, 1
	s_cbranch_scc1 .Lpl_sf_33
	v_pk_add_f32 v[32:33], v[32:33], v[50:51] neg_lo:[0,1] neg_hi:[0,1]
	v_pk_add_f32 v[34:35], v[34:35], v[52:53] neg_lo:[0,1] neg_hi:[0,1]
	v_pk_add_f32 v[36:37], v[36:37], v[54:55] neg_lo:[0,1] neg_hi:[0,1]
	v_pk_add_f32 v[38:39], v[38:39], v[56:57] neg_lo:[0,1] neg_hi:[0,1]
	s_branch .Lpl_se_34

.Lpl_se_34:
	v_lshlrev_b32_e32 v40, 16, v4
	v_and_b32_e32 v41, 0xffff0000, v4
	v_lshlrev_b32_e32 v42, 16, v5
	v_and_b32_e32 v43, 0xffff0000, v5
	v_lshlrev_b32_e32 v44, 16, v6
	v_and_b32_e32 v45, 0xffff0000, v6
	v_lshlrev_b32_e32 v46, 16, v7
	v_and_b32_e32 v47, 0xffff0000, v7
	v_pk_add_f32 v[32:33], v[32:33], v[40:41]
	v_pk_add_f32 v[34:35], v[34:35], v[42:43]
	v_pk_add_f32 v[36:37], v[36:37], v[44:45]
	v_pk_add_f32 v[38:39], v[38:39], v[46:47]
	v_pk_fma_f32 v[82:83], v[32:33], v[94:95], v[40:41] neg_lo:[0,0,1] neg_hi:[0,0,1]
	v_pk_fma_f32 v[84:85], v[34:35], v[94:95], v[42:43] neg_lo:[0,0,1] neg_hi:[0,0,1]
	v_pk_fma_f32 v[86:87], v[36:37], v[94:95], v[44:45] neg_lo:[0,0,1] neg_hi:[0,0,1]
	v_pk_fma_f32 v[88:89], v[38:39], v[94:95], v[46:47] neg_lo:[0,0,1] neg_hi:[0,0,1]
	v_cvt_pk_bf16_f32 v90, v82, v83
	v_cvt_pk_bf16_f32 v91, v84, v85
	v_cvt_pk_bf16_f32 v92, v86, v87
	v_cvt_pk_bf16_f32 v93, v88, v89
	global_store_dwordx4 v48, v[90:93], s[22:23] sc1
	s_add_u32 s22, s22, 0x1000
	s_addc_u32 s23, s23, 0
	s_cmp_lt_i32 s43, 2
	s_cbranch_scc1 .Lpl_sf_35
	v_pk_add_f32 v[32:33], v[32:33], v[58:59] neg_lo:[0,1] neg_hi:[0,1]
	v_pk_add_f32 v[34:35], v[34:35], v[60:61] neg_lo:[0,1] neg_hi:[0,1]
	v_pk_add_f32 v[36:37], v[36:37], v[62:63] neg_lo:[0,1] neg_hi:[0,1]
	v_pk_add_f32 v[38:39], v[38:39], v[64:65] neg_lo:[0,1] neg_hi:[0,1]
	s_branch .Lpl_se_36

.Lpl_se_36:
	v_lshlrev_b32_e32 v40, 16, v8
	v_and_b32_e32 v41, 0xffff0000, v8
	v_lshlrev_b32_e32 v42, 16, v9
	v_and_b32_e32 v43, 0xffff0000, v9
	v_lshlrev_b32_e32 v44, 16, v10
	v_and_b32_e32 v45, 0xffff0000, v10
	v_lshlrev_b32_e32 v46, 16, v11
	v_and_b32_e32 v47, 0xffff0000, v11
	v_pk_add_f32 v[32:33], v[32:33], v[40:41]
	v_pk_add_f32 v[34:35], v[34:35], v[42:43]
	v_pk_add_f32 v[36:37], v[36:37], v[44:45]
	v_pk_add_f32 v[38:39], v[38:39], v[46:47]
	v_pk_fma_f32 v[82:83], v[32:33], v[94:95], v[40:41] neg_lo:[0,0,1] neg_hi:[0,0,1]
	v_pk_fma_f32 v[84:85], v[34:35], v[94:95], v[42:43] neg_lo:[0,0,1] neg_hi:[0,0,1]
	v_pk_fma_f32 v[86:87], v[36:37], v[94:95], v[44:45] neg_lo:[0,0,1] neg_hi:[0,0,1]
	v_pk_fma_f32 v[88:89], v[38:39], v[94:95], v[46:47] neg_lo:[0,0,1] neg_hi:[0,0,1]
	v_cvt_pk_bf16_f32 v90, v82, v83
	v_cvt_pk_bf16_f32 v91, v84, v85
	v_cvt_pk_bf16_f32 v92, v86, v87
	v_cvt_pk_bf16_f32 v93, v88, v89
	global_store_dwordx4 v48, v[90:93], s[22:23] sc1
	s_add_u32 s22, s22, 0x1000
	s_addc_u32 s23, s23, 0
	s_cmp_lt_i32 s43, 3
	s_cbranch_scc1 .Lpl_sf_37
	v_pk_add_f32 v[32:33], v[32:33], v[66:67] neg_lo:[0,1] neg_hi:[0,1]
	v_pk_add_f32 v[34:35], v[34:35], v[68:69] neg_lo:[0,1] neg_hi:[0,1]
	v_pk_add_f32 v[36:37], v[36:37], v[70:71] neg_lo:[0,1] neg_hi:[0,1]
	v_pk_add_f32 v[38:39], v[38:39], v[72:73] neg_lo:[0,1] neg_hi:[0,1]
	s_branch .Lpl_se_38

.Lpl_se_38:
	v_lshlrev_b32_e32 v40, 16, v12
	v_and_b32_e32 v41, 0xffff0000, v12
	v_lshlrev_b32_e32 v42, 16, v13
	v_and_b32_e32 v43, 0xffff0000, v13
	v_lshlrev_b32_e32 v44, 16, v14
	v_and_b32_e32 v45, 0xffff0000, v14
	v_lshlrev_b32_e32 v46, 16, v15
	v_and_b32_e32 v47, 0xffff0000, v15
	v_pk_add_f32 v[32:33], v[32:33], v[40:41]
	v_pk_add_f32 v[34:35], v[34:35], v[42:43]
	v_pk_add_f32 v[36:37], v[36:37], v[44:45]
	v_pk_add_f32 v[38:39], v[38:39], v[46:47]
	v_pk_fma_f32 v[82:83], v[32:33], v[94:95], v[40:41] neg_lo:[0,0,1] neg_hi:[0,0,1]
	v_pk_fma_f32 v[84:85], v[34:35], v[94:95], v[42:43] neg_lo:[0,0,1] neg_hi:[0,0,1]
	v_pk_fma_f32 v[86:87], v[36:37], v[94:95], v[44:45] neg_lo:[0,0,1] neg_hi:[0,0,1]
	v_pk_fma_f32 v[88:89], v[38:39], v[94:95], v[46:47] neg_lo:[0,0,1] neg_hi:[0,0,1]
	v_cvt_pk_bf16_f32 v90, v82, v83
	v_cvt_pk_bf16_f32 v91, v84, v85
	v_cvt_pk_bf16_f32 v92, v86, v87
	v_cvt_pk_bf16_f32 v93, v88, v89
	global_store_dwordx4 v48, v[90:93], s[22:23] sc1
	s_add_u32 s22, s22, 0x1000
	s_addc_u32 s23, s23, 0
	s_cmp_lt_i32 s43, 4
	s_cbranch_scc1 .Lpl_sf_39
	v_pk_add_f32 v[32:33], v[32:33], v[74:75] neg_lo:[0,1] neg_hi:[0,1]
	v_pk_add_f32 v[34:35], v[34:35], v[76:77] neg_lo:[0,1] neg_hi:[0,1]
	v_pk_add_f32 v[36:37], v[36:37], v[78:79] neg_lo:[0,1] neg_hi:[0,1]
	v_pk_add_f32 v[38:39], v[38:39], v[80:81] neg_lo:[0,1] neg_hi:[0,1]
	s_branch .Lpl_se_40

.Lpl_oe_48:
	s_waitcnt vmcnt(0)
	v_lshlrev_b32_e32 v40, 16, v16
	v_and_b32_e32 v41, 0xffff0000, v16
	v_lshlrev_b32_e32 v42, 16, v17
	v_and_b32_e32 v43, 0xffff0000, v17
	v_lshlrev_b32_e32 v44, 16, v18
	v_and_b32_e32 v45, 0xffff0000, v18
	v_lshlrev_b32_e32 v46, 16, v19
	v_and_b32_e32 v47, 0xffff0000, v19
	v_pk_add_f32 v[32:33], v[32:33], v[40:41]
	v_pk_add_f32 v[34:35], v[34:35], v[42:43]
	v_pk_add_f32 v[36:37], v[36:37], v[44:45]
	v_pk_add_f32 v[38:39], v[38:39], v[46:47]
	v_pk_fma_f32 v[82:83], v[32:33], v[94:95], v[40:41] neg_lo:[0,0,1] neg_hi:[0,0,1]
	v_pk_fma_f32 v[84:85], v[34:35], v[94:95], v[42:43] neg_lo:[0,0,1] neg_hi:[0,0,1]
	v_pk_fma_f32 v[86:87], v[36:37], v[94:95], v[44:45] neg_lo:[0,0,1] neg_hi:[0,0,1]
	v_pk_fma_f32 v[88:89], v[38:39], v[94:95], v[46:47] neg_lo:[0,0,1] neg_hi:[0,0,1]
	v_cvt_pk_bf16_f32 v90, v82, v83
	v_cvt_pk_bf16_f32 v91, v84, v85
	v_cvt_pk_bf16_f32 v92, v86, v87
	v_cvt_pk_bf16_f32 v93, v88, v89
	global_store_dwordx4 v48, v[90:93], s[22:23] sc1
	s_add_u32 s22, s22, 0x1000
	s_addc_u32 s23, s23, 0
	s_cmp_lt_i32 s43, 5
	s_cbranch_scc1 .Lpl_sf_49
	v_pk_add_f32 v[32:33], v[32:33], v[50:51] neg_lo:[0,1] neg_hi:[0,1]
	v_pk_add_f32 v[34:35], v[34:35], v[52:53] neg_lo:[0,1] neg_hi:[0,1]
	v_pk_add_f32 v[36:37], v[36:37], v[54:55] neg_lo:[0,1] neg_hi:[0,1]
	v_pk_add_f32 v[38:39], v[38:39], v[56:57] neg_lo:[0,1] neg_hi:[0,1]
	s_branch .Lpl_se_50

.Lpl_se_50:
	v_lshlrev_b32_e32 v40, 16, v20
	v_and_b32_e32 v41, 0xffff0000, v20
	v_lshlrev_b32_e32 v42, 16, v21
	v_and_b32_e32 v43, 0xffff0000, v21
	v_lshlrev_b32_e32 v44, 16, v22
	v_and_b32_e32 v45, 0xffff0000, v22
	v_lshlrev_b32_e32 v46, 16, v23
	v_and_b32_e32 v47, 0xffff0000, v23
	v_pk_add_f32 v[32:33], v[32:33], v[40:41]
	v_pk_add_f32 v[34:35], v[34:35], v[42:43]
	v_pk_add_f32 v[36:37], v[36:37], v[44:45]
	v_pk_add_f32 v[38:39], v[38:39], v[46:47]
	v_pk_fma_f32 v[82:83], v[32:33], v[94:95], v[40:41] neg_lo:[0,0,1] neg_hi:[0,0,1]
	v_pk_fma_f32 v[84:85], v[34:35], v[94:95], v[42:43] neg_lo:[0,0,1] neg_hi:[0,0,1]
	v_pk_fma_f32 v[86:87], v[36:37], v[94:95], v[44:45] neg_lo:[0,0,1] neg_hi:[0,0,1]
	v_pk_fma_f32 v[88:89], v[38:39], v[94:95], v[46:47] neg_lo:[0,0,1] neg_hi:[0,0,1]
	v_cvt_pk_bf16_f32 v90, v82, v83
	v_cvt_pk_bf16_f32 v91, v84, v85
	v_cvt_pk_bf16_f32 v92, v86, v87
	v_cvt_pk_bf16_f32 v93, v88, v89
	global_store_dwordx4 v48, v[90:93], s[22:23] sc1
	s_add_u32 s22, s22, 0x1000
	s_addc_u32 s23, s23, 0
	s_cmp_lt_i32 s43, 6
	s_cbranch_scc1 .Lpl_sf_51
	v_pk_add_f32 v[32:33], v[32:33], v[58:59] neg_lo:[0,1] neg_hi:[0,1]
	v_pk_add_f32 v[34:35], v[34:35], v[60:61] neg_lo:[0,1] neg_hi:[0,1]
	v_pk_add_f32 v[36:37], v[36:37], v[62:63] neg_lo:[0,1] neg_hi:[0,1]
	v_pk_add_f32 v[38:39], v[38:39], v[64:65] neg_lo:[0,1] neg_hi:[0,1]
	s_branch .Lpl_se_52

.Lpl_se_52:
	v_lshlrev_b32_e32 v40, 16, v24
	v_and_b32_e32 v41, 0xffff0000, v24
	v_lshlrev_b32_e32 v42, 16, v25
	v_and_b32_e32 v43, 0xffff0000, v25
	v_lshlrev_b32_e32 v44, 16, v26
	v_and_b32_e32 v45, 0xffff0000, v26
	v_lshlrev_b32_e32 v46, 16, v27
	v_and_b32_e32 v47, 0xffff0000, v27
	v_pk_add_f32 v[32:33], v[32:33], v[40:41]
	v_pk_add_f32 v[34:35], v[34:35], v[42:43]
	v_pk_add_f32 v[36:37], v[36:37], v[44:45]
	v_pk_add_f32 v[38:39], v[38:39], v[46:47]
	v_pk_fma_f32 v[82:83], v[32:33], v[94:95], v[40:41] neg_lo:[0,0,1] neg_hi:[0,0,1]
	v_pk_fma_f32 v[84:85], v[34:35], v[94:95], v[42:43] neg_lo:[0,0,1] neg_hi:[0,0,1]
	v_pk_fma_f32 v[86:87], v[36:37], v[94:95], v[44:45] neg_lo:[0,0,1] neg_hi:[0,0,1]
	v_pk_fma_f32 v[88:89], v[38:39], v[94:95], v[46:47] neg_lo:[0,0,1] neg_hi:[0,0,1]
	v_cvt_pk_bf16_f32 v90, v82, v83
	v_cvt_pk_bf16_f32 v91, v84, v85
	v_cvt_pk_bf16_f32 v92, v86, v87
	v_cvt_pk_bf16_f32 v93, v88, v89
	global_store_dwordx4 v48, v[90:93], s[22:23] sc1
	s_add_u32 s22, s22, 0x1000
	s_addc_u32 s23, s23, 0
	s_cmp_lt_i32 s43, 7
	s_cbranch_scc1 .Lpl_sf_53
	v_pk_add_f32 v[32:33], v[32:33], v[66:67] neg_lo:[0,1] neg_hi:[0,1]
	v_pk_add_f32 v[34:35], v[34:35], v[68:69] neg_lo:[0,1] neg_hi:[0,1]
	v_pk_add_f32 v[36:37], v[36:37], v[70:71] neg_lo:[0,1] neg_hi:[0,1]
	v_pk_add_f32 v[38:39], v[38:39], v[72:73] neg_lo:[0,1] neg_hi:[0,1]
	s_branch .Lpl_se_54

.Lpl_se_54:
	v_lshlrev_b32_e32 v40, 16, v28
	v_and_b32_e32 v41, 0xffff0000, v28
	v_lshlrev_b32_e32 v42, 16, v29
	v_and_b32_e32 v43, 0xffff0000, v29
	v_lshlrev_b32_e32 v44, 16, v30
	v_and_b32_e32 v45, 0xffff0000, v30
	v_lshlrev_b32_e32 v46, 16, v31
	v_and_b32_e32 v47, 0xffff0000, v31
	v_pk_add_f32 v[32:33], v[32:33], v[40:41]
	v_pk_add_f32 v[34:35], v[34:35], v[42:43]
	v_pk_add_f32 v[36:37], v[36:37], v[44:45]
	v_pk_add_f32 v[38:39], v[38:39], v[46:47]
	v_pk_fma_f32 v[82:83], v[32:33], v[94:95], v[40:41] neg_lo:[0,0,1] neg_hi:[0,0,1]
	v_pk_fma_f32 v[84:85], v[34:35], v[94:95], v[42:43] neg_lo:[0,0,1] neg_hi:[0,0,1]
	v_pk_fma_f32 v[86:87], v[36:37], v[94:95], v[44:45] neg_lo:[0,0,1] neg_hi:[0,0,1]
	v_pk_fma_f32 v[88:89], v[38:39], v[94:95], v[46:47] neg_lo:[0,0,1] neg_hi:[0,0,1]
	v_cvt_pk_bf16_f32 v90, v82, v83
	v_cvt_pk_bf16_f32 v91, v84, v85
	v_cvt_pk_bf16_f32 v92, v86, v87
	v_cvt_pk_bf16_f32 v93, v88, v89
	global_store_dwordx4 v48, v[90:93], s[22:23] sc1
	s_add_u32 s22, s22, 0x1000
	s_addc_u32 s23, s23, 0
	s_cmp_lt_i32 s43, 8
	s_cbranch_scc1 .Lpl_sf_55
	v_pk_add_f32 v[32:33], v[32:33], v[74:75] neg_lo:[0,1] neg_hi:[0,1]
	v_pk_add_f32 v[34:35], v[34:35], v[76:77] neg_lo:[0,1] neg_hi:[0,1]
	v_pk_add_f32 v[36:37], v[36:37], v[78:79] neg_lo:[0,1] neg_hi:[0,1]
	v_pk_add_f32 v[38:39], v[38:39], v[80:81] neg_lo:[0,1] neg_hi:[0,1]
	s_branch .Lpl_se_56

.LBB0_821:
	v_mov_b32_e32 v34, v155
	s_or_b64 s[0:1], s[46:47], s[0:1]
	v_ashrrev_i32_e32 v35, 3, v34
	v_and_b32_e32 v32, 0xffffc, v35
	v_and_b32_e32 v33, 31, v34
	v_add_lshl_u32 v32, v32, s6, 11
	v_or3_b32 v32, v32, s28, v33
	v_or_b32_e32 v36, s22, v33
	v_add_u32_e32 v33, s27, v35
	v_lshlrev_b32_e32 v35, 1, v35
	v_mul_u32_u24_e32 v36, 0x110, v36
	v_and_b32_e32 v35, 8, v35
	v_lshrrev_b32_e32 v34, 1, v34
	v_add3_u32 v35, 0, v36, v35
	v_lshrrev_b32_e32 v44, 3, v33
	v_lshlrev_b32_e32 v32, 1, v32
	v_add_u32_e32 v45, 1, v44
	v_add_u32_e32 v46, 2, v44
	v_add_u32_e32 v47, 3, v44
	v_xor_b32_e32 v44, v44, v34
	v_xor_b32_e32 v45, v45, v34
	v_xor_b32_e32 v46, v46, v34
	v_xor_b32_e32 v47, v47, v34
	v_and_b32_e32 v44, 15, v44
	v_and_b32_e32 v45, 15, v45
	v_and_b32_e32 v46, 15, v46
	v_and_b32_e32 v47, 15, v47
	v_lshl_add_u32 v44, v44, 4, v35
	v_lshl_add_u32 v45, v45, 4, v35
	v_lshl_add_u32 v46, v46, 4, v35
	v_lshl_add_u32 v47, v47, 4, v35
	ds_read_b64 v[36:37], v44
	ds_read_b64 v[38:39], v45
	ds_read_b64 v[40:41], v46
	ds_read_b64 v[42:43], v47
	s_add_i32 s35, s35, 1
	s_waitcnt vmcnt(0)
	v_lshlrev_b32_e32 v175, 16, v175
	v_lshlrev_b32_e32 v174, 16, v174
	v_lshlrev_b32_e32 v173, 16, v173
	v_lshlrev_b32_e32 v172, 16, v172
	v_lshlrev_b32_e32 v171, 16, v171
	v_lshlrev_b32_e32 v170, 16, v170
	v_lshlrev_b32_e32 v169, 16, v169
	v_lshlrev_b32_e32 v168, 16, v168
	v_lshlrev_b32_e32 v167, 16, v167
	v_lshlrev_b32_e32 v166, 16, v166
	v_lshlrev_b32_e32 v165, 16, v165
	v_lshlrev_b32_e32 v164, 16, v164
	v_lshlrev_b32_e32 v163, 16, v163
	v_lshlrev_b32_e32 v162, 16, v162
	v_lshlrev_b32_e32 v242, 16, v146
	v_lshlrev_b32_e32 v243, 16, v51
	v_pk_mul_f32 v[184:185], v[174:175], s[78:79] op_sel_hi:[1,0]
	v_pk_mul_f32 v[186:187], v[172:173], s[78:79] op_sel_hi:[1,0]
	v_pk_mul_f32 v[188:189], v[170:171], s[78:79] op_sel_hi:[1,0]
	v_pk_mul_f32 v[190:191], v[168:169], s[78:79] op_sel_hi:[1,0]
	v_pk_mul_f32 v[192:193], v[166:167], s[78:79] op_sel_hi:[1,0]
	v_pk_mul_f32 v[194:195], v[164:165], s[78:79] op_sel_hi:[1,0]
	v_pk_mul_f32 v[196:197], v[162:163], s[78:79] op_sel_hi:[1,0]
	v_pk_mul_f32 v[244:245], v[242:243], s[78:79] op_sel_hi:[1,0]
	v_exp_f32_e32 v184, v184
	v_exp_f32_e32 v185, v185
	v_exp_f32_e32 v186, v186
	v_exp_f32_e32 v187, v187
	v_exp_f32_e32 v188, v188
	v_exp_f32_e32 v189, v189
	v_exp_f32_e32 v190, v190
	v_exp_f32_e32 v191, v191
	v_exp_f32_e32 v192, v192
	v_exp_f32_e32 v193, v193
	v_exp_f32_e32 v194, v194
	v_exp_f32_e32 v195, v195
	v_exp_f32_e32 v196, v196
	v_exp_f32_e32 v197, v197
	v_exp_f32_e32 v244, v244
	v_exp_f32_e32 v245, v245
	s_waitcnt lgkmcnt(0)
	v_lshlrev_b32_e32 v96, 16, v36
	v_and_b32_e32 v97, 0xffff0000, v36
	v_lshlrev_b32_e32 v98, 16, v37
	v_and_b32_e32 v99, 0xffff0000, v37
	v_lshlrev_b32_e32 v100, 16, v38
	v_and_b32_e32 v101, 0xffff0000, v38
	v_lshlrev_b32_e32 v102, 16, v39
	v_and_b32_e32 v103, 0xffff0000, v39
	v_lshlrev_b32_e32 v104, 16, v40
	v_and_b32_e32 v105, 0xffff0000, v40
	v_lshlrev_b32_e32 v106, 16, v41
	v_and_b32_e32 v107, 0xffff0000, v41
	v_lshlrev_b32_e32 v108, 16, v42
	v_and_b32_e32 v109, 0xffff0000, v42
	v_lshlrev_b32_e32 v110, 16, v43
	v_and_b32_e32 v111, 0xffff0000, v43
	v_pk_add_f32 v[184:185], v[184:185], 1.0 op_sel_hi:[1,0]
	v_pk_add_f32 v[186:187], v[186:187], 1.0 op_sel_hi:[1,0]
	v_pk_add_f32 v[188:189], v[188:189], 1.0 op_sel_hi:[1,0]
	v_pk_add_f32 v[190:191], v[190:191], 1.0 op_sel_hi:[1,0]
	v_pk_add_f32 v[192:193], v[192:193], 1.0 op_sel_hi:[1,0]
	v_pk_add_f32 v[194:195], v[194:195], 1.0 op_sel_hi:[1,0]
	v_pk_add_f32 v[196:197], v[196:197], 1.0 op_sel_hi:[1,0]
	v_pk_add_f32 v[244:245], v[244:245], 1.0 op_sel_hi:[1,0]
	v_pk_fma_f32 v[16:17], v[96:97], v[148:149], v[16:17] op_sel_hi:[1,0,1]
	v_pk_fma_f32 v[18:19], v[98:99], v[148:149], v[18:19] op_sel_hi:[1,0,1]
	v_pk_fma_f32 v[20:21], v[100:101], v[148:149], v[20:21] op_sel_hi:[1,0,1]
	v_pk_fma_f32 v[22:23], v[102:103], v[148:149], v[22:23] op_sel_hi:[1,0,1]
	v_pk_fma_f32 v[24:25], v[104:105], v[148:149], v[24:25] op_sel_hi:[1,0,1]
	v_pk_fma_f32 v[26:27], v[106:107], v[148:149], v[26:27] op_sel_hi:[1,0,1]
	v_pk_fma_f32 v[28:29], v[108:109], v[148:149], v[28:29] op_sel_hi:[1,0,1]
	v_pk_fma_f32 v[30:31], v[110:111], v[148:149], v[30:31] op_sel_hi:[1,0,1]
	v_rcp_f32_e32 v184, v184
	v_rcp_f32_e32 v185, v185
	v_rcp_f32_e32 v186, v186
	v_rcp_f32_e32 v187, v187
	v_rcp_f32_e32 v188, v188
	v_rcp_f32_e32 v189, v189
	v_rcp_f32_e32 v190, v190
	v_rcp_f32_e32 v191, v191
	v_rcp_f32_e32 v192, v192
	v_rcp_f32_e32 v193, v193
	v_rcp_f32_e32 v194, v194
	v_rcp_f32_e32 v195, v195
	v_rcp_f32_e32 v196, v196
	v_rcp_f32_e32 v197, v197
	v_rcp_f32_e32 v244, v244
	v_rcp_f32_e32 v245, v245
	s_nop 0
	v_pk_mul_f32 v[184:185], v[174:175], v[184:185]
	v_pk_mul_f32 v[186:187], v[172:173], v[186:187]
	v_pk_mul_f32 v[188:189], v[170:171], v[188:189]
	v_pk_mul_f32 v[190:191], v[168:169], v[190:191]
	v_pk_mul_f32 v[192:193], v[166:167], v[192:193]
	v_pk_mul_f32 v[194:195], v[164:165], v[194:195]
	v_pk_mul_f32 v[196:197], v[162:163], v[196:197]
	v_pk_mul_f32 v[244:245], v[242:243], v[244:245]
	v_pk_mul_f32 v[16:17], v[16:17], v[184:185] op_sel:[0,1] op_sel_hi:[1,0]
	v_pk_mul_f32 v[18:19], v[18:19], v[186:187] op_sel:[0,1] op_sel_hi:[1,0]
	v_pk_mul_f32 v[20:21], v[20:21], v[188:189] op_sel:[0,1] op_sel_hi:[1,0]
	v_pk_mul_f32 v[22:23], v[22:23], v[190:191] op_sel:[0,1] op_sel_hi:[1,0]
	v_pk_mul_f32 v[24:25], v[24:25], v[192:193] op_sel:[0,1] op_sel_hi:[1,0]
	v_pk_mul_f32 v[26:27], v[26:27], v[194:195] op_sel:[0,1] op_sel_hi:[1,0]
	v_pk_mul_f32 v[28:29], v[28:29], v[196:197] op_sel:[0,1] op_sel_hi:[1,0]
	v_pk_mul_f32 v[30:31], v[30:31], v[244:245]
	v_cvt_pk_bf16_f32 v16, v16, v49
	v_cvt_pk_bf16_f32 v17, v17, v49
	v_cvt_pk_bf16_f32 v18, v18, v49
	v_cvt_pk_bf16_f32 v19, v19, v49
	v_cvt_pk_bf16_f32 v20, v20, v49
	v_cvt_pk_bf16_f32 v21, v21, v49
	v_cvt_pk_bf16_f32 v22, v22, v49
	v_cvt_pk_bf16_f32 v23, v23, v49
	v_cvt_pk_bf16_f32 v24, v24, v49
	v_cvt_pk_bf16_f32 v25, v25, v49
	v_cvt_pk_bf16_f32 v26, v26, v49
	v_cvt_pk_bf16_f32 v27, v27, v49
	v_cvt_pk_bf16_f32 v28, v28, v49
	v_cvt_pk_bf16_f32 v29, v29, v49
	v_cvt_pk_bf16_f32 v30, v30, v49
	v_cvt_pk_bf16_f32 v31, v31, v49
	global_store_short v32, v16, s[70:71] sc1
	s_add_u32 s100, s70, 0x1000
	s_addc_u32 s101, s71, 0
	global_store_short v32, v17, s[100:101] sc1
	s_add_u32 s100, s70, 0x2000
	s_addc_u32 s101, s71, 0
	global_store_short v32, v18, s[100:101] sc1
	s_add_u32 s100, s70, 0x3000
	s_addc_u32 s101, s71, 0
	global_store_short v32, v19, s[100:101] sc1
	s_add_u32 s100, s70, 0x8000
	s_addc_u32 s101, s71, 0
	global_store_short v32, v20, s[100:101] sc1
	s_add_u32 s100, s70, 0x9000
	s_addc_u32 s101, s71, 0
	global_store_short v32, v21, s[100:101] sc1
	s_add_u32 s100, s70, 0xa000
	s_addc_u32 s101, s71, 0
	global_store_short v32, v22, s[100:101] sc1
	s_add_u32 s100, s70, 0xb000
	s_addc_u32 s101, s71, 0
	global_store_short v32, v23, s[100:101] sc1
	s_add_u32 s100, s70, 0x10000
	s_addc_u32 s101, s71, 0
	global_store_short v32, v24, s[100:101] sc1
	s_add_u32 s100, s70, 0x11000
	s_addc_u32 s101, s71, 0
	global_store_short v32, v25, s[100:101] sc1
	s_add_u32 s100, s70, 0x12000
	s_addc_u32 s101, s71, 0
	global_store_short v32, v26, s[100:101] sc1
	s_add_u32 s100, s70, 0x13000
	s_addc_u32 s101, s71, 0
	global_store_short v32, v27, s[100:101] sc1
	s_add_u32 s100, s70, 0x18000
	s_addc_u32 s101, s71, 0
	global_store_short v32, v28, s[100:101] sc1
	s_add_u32 s100, s70, 0x19000
	s_addc_u32 s101, s71, 0
	global_store_short v32, v29, s[100:101] sc1
	s_add_u32 s100, s70, 0x1a000
	s_addc_u32 s101, s71, 0
	global_store_short v32, v30, s[100:101] sc1
	s_add_u32 s100, s70, 0x1b000
	s_addc_u32 s101, s71, 0
	global_store_short v32, v31, s[100:101] sc1
	s_and_b64 vcc, exec, s[0:1]
	s_cbranch_vccnz .LBB0_780
	v_add_f32_e32 v146, v149, v156
	v_mov_b32_e32 v16, v155
	v_cmp_nlt_f32_e32 vcc, s19, v146
	s_and_saveexec_b64 s[0:1], vcc
	s_cbranch_execz .LBB0_824
	v_mul_f32_e32 v17, 0x3fb8aa3b, v146
	v_exp_f32_e32 v17, v17
	s_mov_b32 s6, 0x3f317218
	v_add_f32_e32 v20, 1.0, v17
	v_frexp_mant_f32_e32 v22, v20
	v_cvt_f64_f32_e32 v[18:19], v20
	v_frexp_exp_i32_f64_e32 v18, v[18:19]
	v_cmp_gt_f32_e32 vcc, s64, v22
	v_add_f32_e32 v21, -1.0, v20
	v_sub_f32_e32 v23, v21, v20
	v_subbrev_co_u32_e32 v26, vcc, 0, v18, vcc
	v_sub_u32_e32 v18, 0, v26
	v_sub_f32_e32 v21, v17, v21
	v_add_f32_e32 v23, 1.0, v23
	v_ldexp_f32 v19, v20, v18
	v_add_f32_e32 v21, v21, v23
	v_add_f32_e32 v20, -1.0, v19
	v_add_f32_e32 v22, 1.0, v19
	v_ldexp_f32 v18, v21, v18
	v_add_f32_e32 v21, 1.0, v20
	v_add_f32_e32 v23, -1.0, v22
	v_sub_f32_e32 v21, v19, v21
	v_sub_f32_e32 v19, v19, v23
	v_add_f32_e32 v21, v18, v21
	v_add_f32_e32 v18, v18, v19
	v_add_f32_e32 v27, v22, v18
	v_rcp_f32_e32 v29, v27
	v_sub_f32_e32 v19, v27, v22
	v_sub_f32_e32 v28, v18, v19
	v_add_f32_e32 v19, v20, v21
	v_mul_f32_e32 v31, v19, v29
	v_sub_f32_e32 v18, v19, v20
	v_mul_f32_e32 v20, v27, v31
	v_fma_f32 v22, v31, v27, -v20
	v_fmac_f32_e32 v22, v31, v28
	v_sub_f32_e32 v30, v21, v18
	v_add_f32_e32 v18, v20, v22
	v_sub_f32_e32 v21, v19, v18
	v_pk_add_f32 v[24:25], v[18:19], v[20:21] neg_lo:[0,1] neg_hi:[0,1]
	v_mov_b32_e32 v23, v18
	v_pk_add_f32 v[18:19], v[24:25], v[22:23] neg_lo:[0,1] neg_hi:[0,1]
	s_nop 0
	v_add_f32_e32 v19, v30, v19
	v_add_f32_e32 v18, v18, v19
	v_add_f32_e32 v19, v21, v18
	v_mul_f32_e32 v30, v29, v19
	v_mul_f32_e32 v20, v27, v30
	v_fma_f32 v22, v30, v27, -v20
	v_fmac_f32_e32 v22, v30, v28
	v_sub_f32_e32 v21, v21, v19
	v_add_f32_e32 v27, v18, v21
	v_add_f32_e32 v18, v20, v22
	v_sub_f32_e32 v21, v19, v18
	v_pk_add_f32 v[24:25], v[18:19], v[20:21] neg_lo:[0,1] neg_hi:[0,1]
	v_mov_b32_e32 v23, v18
	v_pk_add_f32 v[18:19], v[24:25], v[22:23] neg_lo:[0,1] neg_hi:[0,1]
	s_nop 0
	v_add_f32_e32 v19, v27, v19
	v_add_f32_e32 v18, v18, v19
	v_add_f32_e32 v19, v31, v30
	v_add_f32_e32 v18, v21, v18
	v_sub_f32_e32 v20, v19, v31
	v_mul_f32_e32 v18, v29, v18
	v_sub_f32_e32 v20, v30, v20
	v_add_f32_e32 v20, v20, v18
	v_add_f32_e32 v22, v19, v20
	v_mul_f32_e32 v23, v22, v22
	v_fmamk_f32 v18, v23, 0x3e9b6dac, v236
	v_fmaak_f32 v207, v23, v18, 0x3f2aaada
	v_cvt_f32_i32_e32 v18, v26
	v_sub_f32_e32 v19, v22, v19
	v_sub_f32_e32 v19, v20, v19
	v_ldexp_f32 v24, v19, 1
	v_mul_f32_e32 v19, v22, v23
	v_ldexp_f32 v21, v22, 1
	v_pk_mul_f32 v[22:23], v[18:19], v[206:207]
	s_nop 0
	v_fma_f32 v20, v18, s6, -v22
	v_fmac_f32_e32 v20, 0xb102e308, v18
	v_pk_add_f32 v[18:19], v[22:23], v[20:21]
	s_mov_b32 s6, 0x7f800000
	v_sub_f32_e32 v21, v19, v21
	v_sub_f32_e32 v21, v23, v21
	v_add_f32_e32 v25, v24, v21
	v_mov_b32_e32 v24, v22
	v_pk_add_f32 v[22:23], v[18:19], v[22:23] neg_lo:[0,1] neg_hi:[0,1]
	v_pk_add_f32 v[26:27], v[18:19], v[24:25]
	v_mov_b32_e32 v21, v18
	v_mov_b32_e32 v23, v27
	v_pk_add_f32 v[28:29], v[20:21], v[22:23] neg_lo:[0,1] neg_hi:[0,1]
	v_pk_add_f32 v[20:21], v[20:21], v[22:23]
	v_mov_b32_e32 v24, v25
	v_pk_add_f32 v[22:23], v[20:21], v[18:19] op_sel:[1,0] op_sel_hi:[0,1] neg_lo:[0,1] neg_hi:[0,1]
	v_pk_add_f32 v[30:31], v[26:27], v[22:23] op_sel_hi:[1,0] neg_lo:[0,1] neg_hi:[0,1]
	v_mov_b32_e32 v26, v27
	v_mov_b32_e32 v27, v21
	v_pk_mov_b32 v[22:23], v[18:19], v[22:23] op_sel:[1,0]
	v_mov_b32_e32 v25, v18
	v_pk_add_f32 v[22:23], v[26:27], v[22:23] neg_lo:[0,1] neg_hi:[0,1]
	v_mov_b32_e32 v30, v28
	v_pk_add_f32 v[18:19], v[24:25], v[22:23] neg_lo:[0,1] neg_hi:[0,1]
	v_mov_b32_e32 v29, v21
	v_pk_add_f32 v[22:23], v[30:31], v[18:19]
	v_cmp_neq_f32_e32 vcc, s6, v17
	v_pk_add_f32 v[24:25], v[22:23], v[22:23] op_sel:[0,1] op_sel_hi:[1,0]
	s_mov_b32 s6, 0x33800000
	v_pk_add_f32 v[20:21], v[20:21], v[24:25] op_sel:[1,0] op_sel_hi:[0,1]
	v_mov_b32_e32 v23, v20
	v_pk_add_f32 v[26:27], v[22:23], v[28:29] neg_lo:[0,1] neg_hi:[0,1]
	v_mov_b32_e32 v19, v24
	v_sub_f32_e32 v21, v22, v26
	v_pk_add_f32 v[18:19], v[18:19], v[26:27] neg_lo:[0,1] neg_hi:[0,1]
	v_sub_f32_e32 v21, v28, v21
	v_add_f32_e32 v18, v18, v21
	v_add_f32_e32 v18, v18, v19
	v_add_f32_e32 v18, v20, v18
	v_cndmask_b32_e32 v18, v237, v18, vcc
	v_cmp_ngt_f32_e32 vcc, -1.0, v17
	s_nop 1
	v_cndmask_b32_e32 v18, v238, v18, vcc
	v_cmp_neq_f32_e32 vcc, -1.0, v17
	s_nop 1
	v_cndmask_b32_e32 v18, v239, v18, vcc
	v_cmp_lt_f32_e64 vcc, |v17|, s6
	s_nop 1
	v_cndmask_b32_e32 v146, v18, v17, vcc

.Lsm_nopf:
	global_store_short v[132:133], v48, off sc1
	global_store_dwordx4 v[130:131], v[102:105], off sc1
	global_store_dwordx4 v[130:131], v[110:113], off offset:128 sc1
	global_store_dwordx4 v[130:131], v[118:121], off offset:256 sc1
	global_store_dwordx4 v[130:131], v[126:129], off offset:384 sc1
	s_nop 1
	v_mov_b64_e32 v[112:113], v[26:27]
	v_mov_b64_e32 v[128:129], v[30:31]
	v_mov_b64_e32 v[120:121], v[60:61]
	v_mov_b64_e32 v[126:127], v[28:29]
	v_mov_b64_e32 v[110:111], v[24:25]
	v_mov_b64_e32 v[118:119], v[58:59]
	v_mov_b64_e32 v[136:137], v[64:65]
	v_mov_b64_e32 v[134:135], v[62:63]
	v_add_co_u32_e32 v102, vcc, s17, v130
	s_nop 1
	v_addc_co_u32_e32 v103, vcc, 0, v131, vcc
	global_store_short v[132:133], v140, off offset:128 sc1
	global_store_dwordx4 v[102:103], v[98:101], off sc1
	global_store_dwordx4 v[102:103], v[106:109], off offset:128 sc1
	global_store_dwordx4 v[102:103], v[114:117], off offset:256 sc1
	global_store_dwordx4 v[102:103], v[122:125], off offset:384 sc1
	s_nop 1
	v_add_co_u32_e32 v100, vcc, s13, v130
	s_nop 1
	v_addc_co_u32_e32 v101, vcc, 0, v131, vcc
	v_mov_b64_e32 v[124:125], v[14:15]
	v_mov_b64_e32 v[108:109], v[10:11]
	v_mov_b64_e32 v[116:117], v[42:43]
	v_mov_b64_e32 v[104:105], v[56:57]
	v_mov_b64_e32 v[122:123], v[12:13]
	v_mov_b64_e32 v[106:107], v[8:9]
	v_mov_b64_e32 v[114:115], v[40:41]
	v_mov_b64_e32 v[102:103], v[54:55]
	global_store_short v[132:133], v139, off offset:256 sc1
	global_store_dwordx4 v[100:101], v[82:85], off sc1
	global_store_dwordx4 v[100:101], v[86:89], off offset:128 sc1
	global_store_dwordx4 v[100:101], v[90:93], off offset:256 sc1
	global_store_dwordx4 v[100:101], v[94:97], off offset:384 sc1
	s_nop 1
	v_mov_b64_e32 v[92:93], v[6:7]
	v_mov_b64_e32 v[96:97], v[22:23]
	v_mov_b64_e32 v[88:89], v[52:53]
	v_mov_b64_e32 v[90:91], v[4:5]
	v_mov_b64_e32 v[94:95], v[20:21]
	v_mov_b64_e32 v[86:87], v[50:51]
	v_mov_b64_e32 v[100:101], v[38:39]
	v_mov_b64_e32 v[98:99], v[36:37]
	v_add_co_u32_e32 v82, vcc, s37, v130
	s_nop 1
	v_addc_co_u32_e32 v83, vcc, 0, v131, vcc
	global_store_short v[132:133], v138, off offset:384 sc1
	global_store_dwordx4 v[82:83], v[66:69], off sc1
	global_store_dwordx4 v[82:83], v[70:73], off offset:128 sc1
	global_store_dwordx4 v[82:83], v[74:77], off offset:256 sc1
	global_store_dwordx4 v[82:83], v[78:81], off offset:384 sc1
	s_nop 1
	v_mov_b64_e32 v[132:133], v[46:47]
	v_mov_b64_e32 v[76:77], v[2:3]
	v_mov_b64_e32 v[80:81], v[18:19]
	v_mov_b64_e32 v[84:85], v[34:35]
	s_andn2_b64 vcc, exec, s[40:41]
	v_mov_b64_e32 v[74:75], v[0:1]
	v_mov_b64_e32 v[78:79], v[16:17]
	v_mov_b64_e32 v[130:131], v[44:45]
	v_mov_b64_e32 v[82:83], v[32:33]
	s_cbranch_vccz .LBB0_841

.Lsn_loop:
	v_lshlrev_b32_e32 v114, 16, v50
	v_and_b32_e32 v115, 0xffff0000, v50
	v_lshlrev_b32_e32 v116, 16, v51
	v_and_b32_e32 v117, 0xffff0000, v51
	v_lshlrev_b32_e32 v118, 16, v52
	v_and_b32_e32 v119, 0xffff0000, v52
	v_lshlrev_b32_e32 v120, 16, v53
	v_and_b32_e32 v121, 0xffff0000, v53
	v_lshlrev_b32_e32 v122, 16, v54
	v_and_b32_e32 v123, 0xffff0000, v54
	v_lshlrev_b32_e32 v124, 16, v55
	v_and_b32_e32 v125, 0xffff0000, v55
	v_lshlrev_b32_e32 v126, 16, v56
	v_and_b32_e32 v127, 0xffff0000, v56
	v_lshlrev_b32_e32 v128, 16, v57
	v_and_b32_e32 v129, 0xffff0000, v57
	v_lshlrev_b32_e32 v130, 16, v58
	v_and_b32_e32 v131, 0xffff0000, v58
	v_lshlrev_b32_e32 v132, 16, v59
	v_and_b32_e32 v133, 0xffff0000, v59
	v_lshlrev_b32_e32 v134, 16, v60
	v_and_b32_e32 v135, 0xffff0000, v60
	v_lshlrev_b32_e32 v136, 16, v61
	v_and_b32_e32 v137, 0xffff0000, v61
	v_lshlrev_b32_e32 v138, 16, v62
	v_and_b32_e32 v139, 0xffff0000, v62
	v_lshlrev_b32_e32 v140, 16, v63
	v_and_b32_e32 v141, 0xffff0000, v63
	v_lshlrev_b32_e32 v142, 16, v64
	v_and_b32_e32 v143, 0xffff0000, v64
	v_lshlrev_b32_e32 v144, 16, v65
	v_and_b32_e32 v145, 0xffff0000, v65
	v_lshlrev_b32_e32 v146, 16, v66
	v_and_b32_e32 v147, 0xffff0000, v66
	v_lshlrev_b32_e32 v148, 16, v67
	v_and_b32_e32 v149, 0xffff0000, v67
	v_lshlrev_b32_e32 v150, 16, v68
	v_and_b32_e32 v151, 0xffff0000, v68
	v_lshlrev_b32_e32 v152, 16, v69
	v_and_b32_e32 v153, 0xffff0000, v69
	v_lshlrev_b32_e32 v154, 16, v70
	v_and_b32_e32 v155, 0xffff0000, v70
	v_lshlrev_b32_e32 v156, 16, v71
	v_and_b32_e32 v157, 0xffff0000, v71
	v_lshlrev_b32_e32 v158, 16, v72
	v_and_b32_e32 v159, 0xffff0000, v72
	v_lshlrev_b32_e32 v160, 16, v73
	v_and_b32_e32 v161, 0xffff0000, v73
	v_lshlrev_b32_e32 v162, 16, v74
	v_and_b32_e32 v163, 0xffff0000, v74
	v_lshlrev_b32_e32 v164, 16, v75
	v_and_b32_e32 v165, 0xffff0000, v75
	v_lshlrev_b32_e32 v166, 16, v76
	v_and_b32_e32 v167, 0xffff0000, v76
	v_lshlrev_b32_e32 v168, 16, v77
	v_and_b32_e32 v169, 0xffff0000, v77
	v_lshlrev_b32_e32 v170, 16, v78
	v_and_b32_e32 v171, 0xffff0000, v78
	v_lshlrev_b32_e32 v172, 16, v79
	v_and_b32_e32 v173, 0xffff0000, v79
	v_lshlrev_b32_e32 v174, 16, v80
	v_and_b32_e32 v175, 0xffff0000, v80
	v_lshlrev_b32_e32 v176, 16, v81
	v_and_b32_e32 v177, 0xffff0000, v81
	v_pk_mul_f32 v[178:179], v[114:115], v[114:115]
	v_pk_mul_f32 v[180:181], v[122:123], v[122:123]
	v_pk_mul_f32 v[182:183], v[130:131], v[130:131]
	v_pk_mul_f32 v[184:185], v[138:139], v[138:139]
	v_pk_mul_f32 v[186:187], v[146:147], v[146:147]
	v_pk_mul_f32 v[188:189], v[154:155], v[154:155]
	v_pk_mul_f32 v[190:191], v[162:163], v[162:163]
	v_pk_mul_f32 v[192:193], v[170:171], v[170:171]
	v_pk_fma_f32 v[178:179], v[116:117], v[116:117], v[178:179]
	v_pk_fma_f32 v[180:181], v[124:125], v[124:125], v[180:181]
	v_pk_fma_f32 v[182:183], v[132:133], v[132:133], v[182:183]
	v_pk_fma_f32 v[184:185], v[140:141], v[140:141], v[184:185]
	v_pk_fma_f32 v[186:187], v[148:149], v[148:149], v[186:187]
	v_pk_fma_f32 v[188:189], v[156:157], v[156:157], v[188:189]
	v_pk_fma_f32 v[190:191], v[164:165], v[164:165], v[190:191]
	v_pk_fma_f32 v[192:193], v[172:173], v[172:173], v[192:193]
	v_pk_fma_f32 v[178:179], v[118:119], v[118:119], v[178:179]
	v_pk_fma_f32 v[180:181], v[126:127], v[126:127], v[180:181]
	v_pk_fma_f32 v[182:183], v[134:135], v[134:135], v[182:183]
	v_pk_fma_f32 v[184:185], v[142:143], v[142:143], v[184:185]
	v_pk_fma_f32 v[186:187], v[150:151], v[150:151], v[186:187]
	v_pk_fma_f32 v[188:189], v[158:159], v[158:159], v[188:189]
	v_pk_fma_f32 v[190:191], v[166:167], v[166:167], v[190:191]
	v_pk_fma_f32 v[192:193], v[174:175], v[174:175], v[192:193]
	v_pk_fma_f32 v[178:179], v[120:121], v[120:121], v[178:179]
	v_pk_fma_f32 v[180:181], v[128:129], v[128:129], v[180:181]
	v_pk_fma_f32 v[182:183], v[136:137], v[136:137], v[182:183]
	v_pk_fma_f32 v[184:185], v[144:145], v[144:145], v[184:185]
	v_pk_fma_f32 v[186:187], v[152:153], v[152:153], v[186:187]
	v_pk_fma_f32 v[188:189], v[160:161], v[160:161], v[188:189]
	v_pk_fma_f32 v[190:191], v[168:169], v[168:169], v[190:191]
	v_pk_fma_f32 v[192:193], v[176:177], v[176:177], v[192:193]
	v_add_f32_e32 v178, v178, v179
	v_add_f32_e32 v180, v180, v181
	v_add_f32_e32 v182, v182, v183
	v_add_f32_e32 v184, v184, v185
	v_add_f32_e32 v186, v186, v187
	v_add_f32_e32 v188, v188, v189
	v_add_f32_e32 v190, v190, v191
	v_add_f32_e32 v192, v192, v193
	v_add_f32_dpp v178, v178, v178 quad_perm:[1,0,3,2] row_mask:0xf bank_mask:0xf
	v_add_f32_dpp v180, v180, v180 quad_perm:[1,0,3,2] row_mask:0xf bank_mask:0xf
	v_add_f32_dpp v182, v182, v182 quad_perm:[1,0,3,2] row_mask:0xf bank_mask:0xf
	v_add_f32_dpp v184, v184, v184 quad_perm:[1,0,3,2] row_mask:0xf bank_mask:0xf
	v_add_f32_dpp v186, v186, v186 quad_perm:[1,0,3,2] row_mask:0xf bank_mask:0xf
	v_add_f32_dpp v188, v188, v188 quad_perm:[1,0,3,2] row_mask:0xf bank_mask:0xf
	v_add_f32_dpp v190, v190, v190 quad_perm:[1,0,3,2] row_mask:0xf bank_mask:0xf
	v_add_f32_dpp v192, v192, v192 quad_perm:[1,0,3,2] row_mask:0xf bank_mask:0xf
	v_add_f32_dpp v178, v178, v178 quad_perm:[2,3,0,1] row_mask:0xf bank_mask:0xf
	v_add_f32_dpp v180, v180, v180 quad_perm:[2,3,0,1] row_mask:0xf bank_mask:0xf
	v_add_f32_dpp v182, v182, v182 quad_perm:[2,3,0,1] row_mask:0xf bank_mask:0xf
	v_add_f32_dpp v184, v184, v184 quad_perm:[2,3,0,1] row_mask:0xf bank_mask:0xf
	v_add_f32_dpp v186, v186, v186 quad_perm:[2,3,0,1] row_mask:0xf bank_mask:0xf
	v_add_f32_dpp v188, v188, v188 quad_perm:[2,3,0,1] row_mask:0xf bank_mask:0xf
	v_add_f32_dpp v190, v190, v190 quad_perm:[2,3,0,1] row_mask:0xf bank_mask:0xf
	v_add_f32_dpp v192, v192, v192 quad_perm:[2,3,0,1] row_mask:0xf bank_mask:0xf
	v_add_f32_dpp v178, v178, v178 row_half_mirror row_mask:0xf bank_mask:0xf
	v_add_f32_dpp v180, v180, v180 row_half_mirror row_mask:0xf bank_mask:0xf
	v_add_f32_dpp v182, v182, v182 row_half_mirror row_mask:0xf bank_mask:0xf
	v_add_f32_dpp v184, v184, v184 row_half_mirror row_mask:0xf bank_mask:0xf
	v_add_f32_dpp v186, v186, v186 row_half_mirror row_mask:0xf bank_mask:0xf
	v_add_f32_dpp v188, v188, v188 row_half_mirror row_mask:0xf bank_mask:0xf
	v_add_f32_dpp v190, v190, v190 row_half_mirror row_mask:0xf bank_mask:0xf
	v_add_f32_dpp v192, v192, v192 row_half_mirror row_mask:0xf bank_mask:0xf
	v_add_f32_dpp v178, v178, v178 row_mirror row_mask:0xf bank_mask:0xf
	v_add_f32_dpp v180, v180, v180 row_mirror row_mask:0xf bank_mask:0xf
	v_add_f32_dpp v182, v182, v182 row_mirror row_mask:0xf bank_mask:0xf
	v_add_f32_dpp v184, v184, v184 row_mirror row_mask:0xf bank_mask:0xf
	v_add_f32_dpp v186, v186, v186 row_mirror row_mask:0xf bank_mask:0xf
	v_add_f32_dpp v188, v188, v188 row_mirror row_mask:0xf bank_mask:0xf
	v_add_f32_dpp v190, v190, v190 row_mirror row_mask:0xf bank_mask:0xf
	v_add_f32_dpp v192, v192, v192 row_mirror row_mask:0xf bank_mask:0xf
	ds_bpermute_b32 v179, v4, v178
	ds_bpermute_b32 v181, v4, v180
	ds_bpermute_b32 v183, v4, v182
	ds_bpermute_b32 v185, v4, v184
	ds_bpermute_b32 v187, v4, v186
	ds_bpermute_b32 v189, v4, v188
	ds_bpermute_b32 v191, v4, v190
	ds_bpermute_b32 v193, v4, v192
	s_waitcnt lgkmcnt(7)
	v_add_f32_e32 v178, v178, v179
	s_waitcnt lgkmcnt(6)
	v_add_f32_e32 v180, v180, v181
	s_waitcnt lgkmcnt(5)
	v_add_f32_e32 v182, v182, v183
	s_waitcnt lgkmcnt(4)
	v_add_f32_e32 v184, v184, v185
	s_waitcnt lgkmcnt(3)
	v_add_f32_e32 v186, v186, v187
	s_waitcnt lgkmcnt(2)
	v_add_f32_e32 v188, v188, v189
	s_waitcnt lgkmcnt(1)
	v_add_f32_e32 v190, v190, v191
	s_waitcnt lgkmcnt(0)
	v_add_f32_e32 v192, v192, v193
	v_fmamk_f32 v178, v178, 0x3b800000, v234
	v_fmamk_f32 v180, v180, 0x3b800000, v234
	v_fmamk_f32 v182, v182, 0x3b800000, v234
	v_fmamk_f32 v184, v184, 0x3b800000, v234
	v_fmamk_f32 v186, v186, 0x3b800000, v234
	v_fmamk_f32 v188, v188, 0x3b800000, v234
	v_fmamk_f32 v190, v190, 0x3b800000, v234
	v_fmamk_f32 v192, v192, 0x3b800000, v234
	v_rsq_f32_e32 v178, v178
	v_rsq_f32_e32 v180, v180
	v_rsq_f32_e32 v182, v182
	v_rsq_f32_e32 v184, v184
	v_rsq_f32_e32 v186, v186
	v_rsq_f32_e32 v188, v188
	v_rsq_f32_e32 v190, v190
	v_rsq_f32_e32 v192, v192
	v_pk_mul_f32 v[114:115], v[114:115], v[178:179] op_sel_hi:[1,0]
	v_pk_mul_f32 v[116:117], v[116:117], v[178:179] op_sel_hi:[1,0]
	v_pk_mul_f32 v[118:119], v[118:119], v[178:179] op_sel_hi:[1,0]
	v_pk_mul_f32 v[120:121], v[120:121], v[178:179] op_sel_hi:[1,0]
	v_pk_mul_f32 v[122:123], v[122:123], v[180:181] op_sel_hi:[1,0]
	v_pk_mul_f32 v[124:125], v[124:125], v[180:181] op_sel_hi:[1,0]
	v_pk_mul_f32 v[126:127], v[126:127], v[180:181] op_sel_hi:[1,0]
	v_pk_mul_f32 v[128:129], v[128:129], v[180:181] op_sel_hi:[1,0]
	v_pk_mul_f32 v[130:131], v[130:131], v[182:183] op_sel_hi:[1,0]
	v_pk_mul_f32 v[132:133], v[132:133], v[182:183] op_sel_hi:[1,0]
	v_pk_mul_f32 v[134:135], v[134:135], v[182:183] op_sel_hi:[1,0]
	v_pk_mul_f32 v[136:137], v[136:137], v[182:183] op_sel_hi:[1,0]
	v_pk_mul_f32 v[138:139], v[138:139], v[184:185] op_sel_hi:[1,0]
	v_pk_mul_f32 v[140:141], v[140:141], v[184:185] op_sel_hi:[1,0]
	v_pk_mul_f32 v[142:143], v[142:143], v[184:185] op_sel_hi:[1,0]
	v_pk_mul_f32 v[144:145], v[144:145], v[184:185] op_sel_hi:[1,0]
	v_pk_mul_f32 v[146:147], v[146:147], v[186:187] op_sel_hi:[1,0]
	v_pk_mul_f32 v[148:149], v[148:149], v[186:187] op_sel_hi:[1,0]
	v_pk_mul_f32 v[150:151], v[150:151], v[186:187] op_sel_hi:[1,0]
	v_pk_mul_f32 v[152:153], v[152:153], v[186:187] op_sel_hi:[1,0]
	v_pk_mul_f32 v[154:155], v[154:155], v[188:189] op_sel_hi:[1,0]
	v_pk_mul_f32 v[156:157], v[156:157], v[188:189] op_sel_hi:[1,0]
	v_pk_mul_f32 v[158:159], v[158:159], v[188:189] op_sel_hi:[1,0]
	v_pk_mul_f32 v[160:161], v[160:161], v[188:189] op_sel_hi:[1,0]
	v_pk_mul_f32 v[162:163], v[162:163], v[190:191] op_sel_hi:[1,0]
	v_pk_mul_f32 v[164:165], v[164:165], v[190:191] op_sel_hi:[1,0]
	v_pk_mul_f32 v[166:167], v[166:167], v[190:191] op_sel_hi:[1,0]
	v_pk_mul_f32 v[168:169], v[168:169], v[190:191] op_sel_hi:[1,0]
	v_pk_mul_f32 v[170:171], v[170:171], v[192:193] op_sel_hi:[1,0]
	v_pk_mul_f32 v[172:173], v[172:173], v[192:193] op_sel_hi:[1,0]
	v_pk_mul_f32 v[174:175], v[174:175], v[192:193] op_sel_hi:[1,0]
	v_pk_mul_f32 v[176:177], v[176:177], v[192:193] op_sel_hi:[1,0]
	v_pk_mul_f32 v[114:115], v[114:115], v[8:9]
	v_pk_mul_f32 v[116:117], v[116:117], v[10:11]
	v_pk_mul_f32 v[118:119], v[118:119], v[12:13]
	v_pk_mul_f32 v[120:121], v[120:121], v[14:15]
	v_pk_mul_f32 v[122:123], v[122:123], v[16:17]
	v_pk_mul_f32 v[124:125], v[124:125], v[18:19]
	v_pk_mul_f32 v[126:127], v[126:127], v[20:21]
	v_pk_mul_f32 v[128:129], v[128:129], v[22:23]
	v_pk_mul_f32 v[130:131], v[130:131], v[24:25]
	v_pk_mul_f32 v[132:133], v[132:133], v[26:27]
	v_pk_mul_f32 v[134:135], v[134:135], v[28:29]
	v_pk_mul_f32 v[136:137], v[136:137], v[30:31]
	v_pk_mul_f32 v[138:139], v[138:139], v[32:33]
	v_pk_mul_f32 v[140:141], v[140:141], v[34:35]
	v_pk_mul_f32 v[142:143], v[142:143], v[36:37]
	v_pk_mul_f32 v[144:145], v[144:145], v[38:39]
	v_pk_mul_f32 v[146:147], v[146:147], v[8:9]
	v_pk_mul_f32 v[148:149], v[148:149], v[10:11]
	v_pk_mul_f32 v[150:151], v[150:151], v[12:13]
	v_pk_mul_f32 v[152:153], v[152:153], v[14:15]
	v_pk_mul_f32 v[154:155], v[154:155], v[16:17]
	v_pk_mul_f32 v[156:157], v[156:157], v[18:19]
	v_pk_mul_f32 v[158:159], v[158:159], v[20:21]
	v_pk_mul_f32 v[160:161], v[160:161], v[22:23]
	v_pk_mul_f32 v[162:163], v[162:163], v[24:25]
	v_pk_mul_f32 v[164:165], v[164:165], v[26:27]
	v_pk_mul_f32 v[166:167], v[166:167], v[28:29]
	v_pk_mul_f32 v[168:169], v[168:169], v[30:31]
	v_pk_mul_f32 v[170:171], v[170:171], v[32:33]
	v_pk_mul_f32 v[172:173], v[172:173], v[34:35]
	v_pk_mul_f32 v[174:175], v[174:175], v[36:37]
	v_pk_mul_f32 v[176:177], v[176:177], v[38:39]
	v_cvt_pk_bf16_f32 v50, v114, v115
	v_cvt_pk_bf16_f32 v51, v116, v117
	v_cvt_pk_bf16_f32 v52, v118, v119
	v_cvt_pk_bf16_f32 v53, v120, v121
	v_cvt_pk_bf16_f32 v54, v122, v123
	v_cvt_pk_bf16_f32 v55, v124, v125
	v_cvt_pk_bf16_f32 v56, v126, v127
	v_cvt_pk_bf16_f32 v57, v128, v129
	v_cvt_pk_bf16_f32 v58, v130, v131
	v_cvt_pk_bf16_f32 v59, v132, v133
	v_cvt_pk_bf16_f32 v60, v134, v135
	v_cvt_pk_bf16_f32 v61, v136, v137
	v_cvt_pk_bf16_f32 v62, v138, v139
	v_cvt_pk_bf16_f32 v63, v140, v141
	v_cvt_pk_bf16_f32 v64, v142, v143
	v_cvt_pk_bf16_f32 v65, v144, v145
	v_cvt_pk_bf16_f32 v66, v146, v147
	v_cvt_pk_bf16_f32 v67, v148, v149
	v_cvt_pk_bf16_f32 v68, v150, v151
	v_cvt_pk_bf16_f32 v69, v152, v153
	v_cvt_pk_bf16_f32 v70, v154, v155
	v_cvt_pk_bf16_f32 v71, v156, v157
	v_cvt_pk_bf16_f32 v72, v158, v159
	v_cvt_pk_bf16_f32 v73, v160, v161
	v_cvt_pk_bf16_f32 v74, v162, v163
	v_cvt_pk_bf16_f32 v75, v164, v165
	v_cvt_pk_bf16_f32 v76, v166, v167
	v_cvt_pk_bf16_f32 v77, v168, v169
	v_cvt_pk_bf16_f32 v78, v170, v171
	v_cvt_pk_bf16_f32 v79, v172, v173
	v_cvt_pk_bf16_f32 v80, v174, v175
	v_cvt_pk_bf16_f32 v81, v176, v177
	s_lshl_b32 s23, s22, 12
	s_add_u32 s6, s26, s23
	s_addc_u32 s7, s27, 0
	global_store_dwordx4 v2, v[50:53], s[6:7] offset:0 sc1
	global_store_dwordx4 v2, v[54:57], s[6:7] offset:1024 sc1
	global_store_dwordx4 v2, v[58:61], s[6:7] offset:2048 sc1
	global_store_dwordx4 v2, v[62:65], s[6:7] offset:3072 sc1
	s_add_u32 s6, s6, 0x1000
	s_addc_u32 s7, s7, 0
	global_store_dwordx4 v2, v[66:69], s[6:7] offset:0 sc1
	global_store_dwordx4 v2, v[70:73], s[6:7] offset:1024 sc1
	global_store_dwordx4 v2, v[74:77], s[6:7] offset:2048 sc1
	global_store_dwordx4 v2, v[78:81], s[6:7] offset:3072 sc1
	s_add_u32 s10, s22, 8192
	s_cmp_ge_u32 s10, 0x4400
	s_cselect_b32 s10, s22, s10
	s_lshl_b32 s23, s10, 12
	s_add_u32 s6, s24, s23
	s_addc_u32 s7, s25, 0
	global_load_dwordx4 v[50:53], v2, s[6:7] offset:0
	global_load_dwordx4 v[54:57], v2, s[6:7] offset:1024
	global_load_dwordx4 v[58:61], v2, s[6:7] offset:2048
	global_load_dwordx4 v[62:65], v2, s[6:7] offset:3072
	s_add_u32 s6, s6, 0x1000
	s_addc_u32 s7, s7, 0
	global_load_dwordx4 v[66:69], v2, s[6:7] offset:0
	global_load_dwordx4 v[70:73], v2, s[6:7] offset:1024
	global_load_dwordx4 v[74:77], v2, s[6:7] offset:2048
	global_load_dwordx4 v[78:81], v2, s[6:7] offset:3072
	s_waitcnt vmcnt(16)
	s_add_u32 s10, s22, 4096
	s_cmp_ge_u32 s10, 0x4400
	s_cbranch_scc1 .Lsn_end
	v_lshlrev_b32_e32 v114, 16, v82
	v_and_b32_e32 v115, 0xffff0000, v82
	v_lshlrev_b32_e32 v116, 16, v83
	v_and_b32_e32 v117, 0xffff0000, v83
	v_lshlrev_b32_e32 v118, 16, v84
	v_and_b32_e32 v119, 0xffff0000, v84
	v_lshlrev_b32_e32 v120, 16, v85
	v_and_b32_e32 v121, 0xffff0000, v85
	v_lshlrev_b32_e32 v122, 16, v86
	v_and_b32_e32 v123, 0xffff0000, v86
	v_lshlrev_b32_e32 v124, 16, v87
	v_and_b32_e32 v125, 0xffff0000, v87
	v_lshlrev_b32_e32 v126, 16, v88
	v_and_b32_e32 v127, 0xffff0000, v88
	v_lshlrev_b32_e32 v128, 16, v89
	v_and_b32_e32 v129, 0xffff0000, v89
	v_lshlrev_b32_e32 v130, 16, v90
	v_and_b32_e32 v131, 0xffff0000, v90
	v_lshlrev_b32_e32 v132, 16, v91
	v_and_b32_e32 v133, 0xffff0000, v91
	v_lshlrev_b32_e32 v134, 16, v92
	v_and_b32_e32 v135, 0xffff0000, v92
	v_lshlrev_b32_e32 v136, 16, v93
	v_and_b32_e32 v137, 0xffff0000, v93
	v_lshlrev_b32_e32 v138, 16, v94
	v_and_b32_e32 v139, 0xffff0000, v94
	v_lshlrev_b32_e32 v140, 16, v95
	v_and_b32_e32 v141, 0xffff0000, v95
	v_lshlrev_b32_e32 v142, 16, v96
	v_and_b32_e32 v143, 0xffff0000, v96
	v_lshlrev_b32_e32 v144, 16, v97
	v_and_b32_e32 v145, 0xffff0000, v97
	v_lshlrev_b32_e32 v146, 16, v98
	v_and_b32_e32 v147, 0xffff0000, v98
	v_lshlrev_b32_e32 v148, 16, v99
	v_and_b32_e32 v149, 0xffff0000, v99
	v_lshlrev_b32_e32 v150, 16, v100
	v_and_b32_e32 v151, 0xffff0000, v100
	v_lshlrev_b32_e32 v152, 16, v101
	v_and_b32_e32 v153, 0xffff0000, v101
	v_lshlrev_b32_e32 v154, 16, v102
	v_and_b32_e32 v155, 0xffff0000, v102
	v_lshlrev_b32_e32 v156, 16, v103
	v_and_b32_e32 v157, 0xffff0000, v103
	v_lshlrev_b32_e32 v158, 16, v104
	v_and_b32_e32 v159, 0xffff0000, v104
	v_lshlrev_b32_e32 v160, 16, v105
	v_and_b32_e32 v161, 0xffff0000, v105
	v_lshlrev_b32_e32 v162, 16, v106
	v_and_b32_e32 v163, 0xffff0000, v106
	v_lshlrev_b32_e32 v164, 16, v107
	v_and_b32_e32 v165, 0xffff0000, v107
	v_lshlrev_b32_e32 v166, 16, v108
	v_and_b32_e32 v167, 0xffff0000, v108
	v_lshlrev_b32_e32 v168, 16, v109
	v_and_b32_e32 v169, 0xffff0000, v109
	v_lshlrev_b32_e32 v170, 16, v110
	v_and_b32_e32 v171, 0xffff0000, v110
	v_lshlrev_b32_e32 v172, 16, v111
	v_and_b32_e32 v173, 0xffff0000, v111
	v_lshlrev_b32_e32 v174, 16, v112
	v_and_b32_e32 v175, 0xffff0000, v112
	v_lshlrev_b32_e32 v176, 16, v113
	v_and_b32_e32 v177, 0xffff0000, v113
	v_pk_mul_f32 v[178:179], v[114:115], v[114:115]
	v_pk_mul_f32 v[180:181], v[122:123], v[122:123]
	v_pk_mul_f32 v[182:183], v[130:131], v[130:131]
	v_pk_mul_f32 v[184:185], v[138:139], v[138:139]
	v_pk_mul_f32 v[186:187], v[146:147], v[146:147]
	v_pk_mul_f32 v[188:189], v[154:155], v[154:155]
	v_pk_mul_f32 v[190:191], v[162:163], v[162:163]
	v_pk_mul_f32 v[192:193], v[170:171], v[170:171]
	v_pk_fma_f32 v[178:179], v[116:117], v[116:117], v[178:179]
	v_pk_fma_f32 v[180:181], v[124:125], v[124:125], v[180:181]
	v_pk_fma_f32 v[182:183], v[132:133], v[132:133], v[182:183]
	v_pk_fma_f32 v[184:185], v[140:141], v[140:141], v[184:185]
	v_pk_fma_f32 v[186:187], v[148:149], v[148:149], v[186:187]
	v_pk_fma_f32 v[188:189], v[156:157], v[156:157], v[188:189]
	v_pk_fma_f32 v[190:191], v[164:165], v[164:165], v[190:191]
	v_pk_fma_f32 v[192:193], v[172:173], v[172:173], v[192:193]
	v_pk_fma_f32 v[178:179], v[118:119], v[118:119], v[178:179]
	v_pk_fma_f32 v[180:181], v[126:127], v[126:127], v[180:181]
	v_pk_fma_f32 v[182:183], v[134:135], v[134:135], v[182:183]
	v_pk_fma_f32 v[184:185], v[142:143], v[142:143], v[184:185]
	v_pk_fma_f32 v[186:187], v[150:151], v[150:151], v[186:187]
	v_pk_fma_f32 v[188:189], v[158:159], v[158:159], v[188:189]
	v_pk_fma_f32 v[190:191], v[166:167], v[166:167], v[190:191]
	v_pk_fma_f32 v[192:193], v[174:175], v[174:175], v[192:193]
	v_pk_fma_f32 v[178:179], v[120:121], v[120:121], v[178:179]
	v_pk_fma_f32 v[180:181], v[128:129], v[128:129], v[180:181]
	v_pk_fma_f32 v[182:183], v[136:137], v[136:137], v[182:183]
	v_pk_fma_f32 v[184:185], v[144:145], v[144:145], v[184:185]
	v_pk_fma_f32 v[186:187], v[152:153], v[152:153], v[186:187]
	v_pk_fma_f32 v[188:189], v[160:161], v[160:161], v[188:189]
	v_pk_fma_f32 v[190:191], v[168:169], v[168:169], v[190:191]
	v_pk_fma_f32 v[192:193], v[176:177], v[176:177], v[192:193]
	v_add_f32_e32 v178, v178, v179
	v_add_f32_e32 v180, v180, v181
	v_add_f32_e32 v182, v182, v183
	v_add_f32_e32 v184, v184, v185
	v_add_f32_e32 v186, v186, v187
	v_add_f32_e32 v188, v188, v189
	v_add_f32_e32 v190, v190, v191
	v_add_f32_e32 v192, v192, v193
	v_add_f32_dpp v178, v178, v178 quad_perm:[1,0,3,2] row_mask:0xf bank_mask:0xf
	v_add_f32_dpp v180, v180, v180 quad_perm:[1,0,3,2] row_mask:0xf bank_mask:0xf
	v_add_f32_dpp v182, v182, v182 quad_perm:[1,0,3,2] row_mask:0xf bank_mask:0xf
	v_add_f32_dpp v184, v184, v184 quad_perm:[1,0,3,2] row_mask:0xf bank_mask:0xf
	v_add_f32_dpp v186, v186, v186 quad_perm:[1,0,3,2] row_mask:0xf bank_mask:0xf
	v_add_f32_dpp v188, v188, v188 quad_perm:[1,0,3,2] row_mask:0xf bank_mask:0xf
	v_add_f32_dpp v190, v190, v190 quad_perm:[1,0,3,2] row_mask:0xf bank_mask:0xf
	v_add_f32_dpp v192, v192, v192 quad_perm:[1,0,3,2] row_mask:0xf bank_mask:0xf
	v_add_f32_dpp v178, v178, v178 quad_perm:[2,3,0,1] row_mask:0xf bank_mask:0xf
	v_add_f32_dpp v180, v180, v180 quad_perm:[2,3,0,1] row_mask:0xf bank_mask:0xf
	v_add_f32_dpp v182, v182, v182 quad_perm:[2,3,0,1] row_mask:0xf bank_mask:0xf
	v_add_f32_dpp v184, v184, v184 quad_perm:[2,3,0,1] row_mask:0xf bank_mask:0xf
	v_add_f32_dpp v186, v186, v186 quad_perm:[2,3,0,1] row_mask:0xf bank_mask:0xf
	v_add_f32_dpp v188, v188, v188 quad_perm:[2,3,0,1] row_mask:0xf bank_mask:0xf
	v_add_f32_dpp v190, v190, v190 quad_perm:[2,3,0,1] row_mask:0xf bank_mask:0xf
	v_add_f32_dpp v192, v192, v192 quad_perm:[2,3,0,1] row_mask:0xf bank_mask:0xf
	v_add_f32_dpp v178, v178, v178 row_half_mirror row_mask:0xf bank_mask:0xf
	v_add_f32_dpp v180, v180, v180 row_half_mirror row_mask:0xf bank_mask:0xf
	v_add_f32_dpp v182, v182, v182 row_half_mirror row_mask:0xf bank_mask:0xf
	v_add_f32_dpp v184, v184, v184 row_half_mirror row_mask:0xf bank_mask:0xf
	v_add_f32_dpp v186, v186, v186 row_half_mirror row_mask:0xf bank_mask:0xf
	v_add_f32_dpp v188, v188, v188 row_half_mirror row_mask:0xf bank_mask:0xf
	v_add_f32_dpp v190, v190, v190 row_half_mirror row_mask:0xf bank_mask:0xf
	v_add_f32_dpp v192, v192, v192 row_half_mirror row_mask:0xf bank_mask:0xf
	v_add_f32_dpp v178, v178, v178 row_mirror row_mask:0xf bank_mask:0xf
	v_add_f32_dpp v180, v180, v180 row_mirror row_mask:0xf bank_mask:0xf
	v_add_f32_dpp v182, v182, v182 row_mirror row_mask:0xf bank_mask:0xf
	v_add_f32_dpp v184, v184, v184 row_mirror row_mask:0xf bank_mask:0xf
	v_add_f32_dpp v186, v186, v186 row_mirror row_mask:0xf bank_mask:0xf
	v_add_f32_dpp v188, v188, v188 row_mirror row_mask:0xf bank_mask:0xf
	v_add_f32_dpp v190, v190, v190 row_mirror row_mask:0xf bank_mask:0xf
	v_add_f32_dpp v192, v192, v192 row_mirror row_mask:0xf bank_mask:0xf
	ds_bpermute_b32 v179, v4, v178
	ds_bpermute_b32 v181, v4, v180
	ds_bpermute_b32 v183, v4, v182
	ds_bpermute_b32 v185, v4, v184
	ds_bpermute_b32 v187, v4, v186
	ds_bpermute_b32 v189, v4, v188
	ds_bpermute_b32 v191, v4, v190
	ds_bpermute_b32 v193, v4, v192
	s_waitcnt lgkmcnt(7)
	v_add_f32_e32 v178, v178, v179
	s_waitcnt lgkmcnt(6)
	v_add_f32_e32 v180, v180, v181
	s_waitcnt lgkmcnt(5)
	v_add_f32_e32 v182, v182, v183
	s_waitcnt lgkmcnt(4)
	v_add_f32_e32 v184, v184, v185
	s_waitcnt lgkmcnt(3)
	v_add_f32_e32 v186, v186, v187
	s_waitcnt lgkmcnt(2)
	v_add_f32_e32 v188, v188, v189
	s_waitcnt lgkmcnt(1)
	v_add_f32_e32 v190, v190, v191
	s_waitcnt lgkmcnt(0)
	v_add_f32_e32 v192, v192, v193
	v_fmamk_f32 v178, v178, 0x3b800000, v234
	v_fmamk_f32 v180, v180, 0x3b800000, v234
	v_fmamk_f32 v182, v182, 0x3b800000, v234
	v_fmamk_f32 v184, v184, 0x3b800000, v234
	v_fmamk_f32 v186, v186, 0x3b800000, v234
	v_fmamk_f32 v188, v188, 0x3b800000, v234
	v_fmamk_f32 v190, v190, 0x3b800000, v234
	v_fmamk_f32 v192, v192, 0x3b800000, v234
	v_rsq_f32_e32 v178, v178
	v_rsq_f32_e32 v180, v180
	v_rsq_f32_e32 v182, v182
	v_rsq_f32_e32 v184, v184
	v_rsq_f32_e32 v186, v186
	v_rsq_f32_e32 v188, v188
	v_rsq_f32_e32 v190, v190
	v_rsq_f32_e32 v192, v192
	v_pk_mul_f32 v[114:115], v[114:115], v[178:179] op_sel_hi:[1,0]
	v_pk_mul_f32 v[116:117], v[116:117], v[178:179] op_sel_hi:[1,0]
	v_pk_mul_f32 v[118:119], v[118:119], v[178:179] op_sel_hi:[1,0]
	v_pk_mul_f32 v[120:121], v[120:121], v[178:179] op_sel_hi:[1,0]
	v_pk_mul_f32 v[122:123], v[122:123], v[180:181] op_sel_hi:[1,0]
	v_pk_mul_f32 v[124:125], v[124:125], v[180:181] op_sel_hi:[1,0]
	v_pk_mul_f32 v[126:127], v[126:127], v[180:181] op_sel_hi:[1,0]
	v_pk_mul_f32 v[128:129], v[128:129], v[180:181] op_sel_hi:[1,0]
	v_pk_mul_f32 v[130:131], v[130:131], v[182:183] op_sel_hi:[1,0]
	v_pk_mul_f32 v[132:133], v[132:133], v[182:183] op_sel_hi:[1,0]
	v_pk_mul_f32 v[134:135], v[134:135], v[182:183] op_sel_hi:[1,0]
	v_pk_mul_f32 v[136:137], v[136:137], v[182:183] op_sel_hi:[1,0]
	v_pk_mul_f32 v[138:139], v[138:139], v[184:185] op_sel_hi:[1,0]
	v_pk_mul_f32 v[140:141], v[140:141], v[184:185] op_sel_hi:[1,0]
	v_pk_mul_f32 v[142:143], v[142:143], v[184:185] op_sel_hi:[1,0]
	v_pk_mul_f32 v[144:145], v[144:145], v[184:185] op_sel_hi:[1,0]
	v_pk_mul_f32 v[146:147], v[146:147], v[186:187] op_sel_hi:[1,0]
	v_pk_mul_f32 v[148:149], v[148:149], v[186:187] op_sel_hi:[1,0]
	v_pk_mul_f32 v[150:151], v[150:151], v[186:187] op_sel_hi:[1,0]
	v_pk_mul_f32 v[152:153], v[152:153], v[186:187] op_sel_hi:[1,0]
	v_pk_mul_f32 v[154:155], v[154:155], v[188:189] op_sel_hi:[1,0]
	v_pk_mul_f32 v[156:157], v[156:157], v[188:189] op_sel_hi:[1,0]
	v_pk_mul_f32 v[158:159], v[158:159], v[188:189] op_sel_hi:[1,0]
	v_pk_mul_f32 v[160:161], v[160:161], v[188:189] op_sel_hi:[1,0]
	v_pk_mul_f32 v[162:163], v[162:163], v[190:191] op_sel_hi:[1,0]
	v_pk_mul_f32 v[164:165], v[164:165], v[190:191] op_sel_hi:[1,0]
	v_pk_mul_f32 v[166:167], v[166:167], v[190:191] op_sel_hi:[1,0]
	v_pk_mul_f32 v[168:169], v[168:169], v[190:191] op_sel_hi:[1,0]
	v_pk_mul_f32 v[170:171], v[170:171], v[192:193] op_sel_hi:[1,0]
	v_pk_mul_f32 v[172:173], v[172:173], v[192:193] op_sel_hi:[1,0]
	v_pk_mul_f32 v[174:175], v[174:175], v[192:193] op_sel_hi:[1,0]
	v_pk_mul_f32 v[176:177], v[176:177], v[192:193] op_sel_hi:[1,0]
	v_pk_mul_f32 v[114:115], v[114:115], v[8:9]
	v_pk_mul_f32 v[116:117], v[116:117], v[10:11]
	v_pk_mul_f32 v[118:119], v[118:119], v[12:13]
	v_pk_mul_f32 v[120:121], v[120:121], v[14:15]
	v_pk_mul_f32 v[122:123], v[122:123], v[16:17]
	v_pk_mul_f32 v[124:125], v[124:125], v[18:19]
	v_pk_mul_f32 v[126:127], v[126:127], v[20:21]
	v_pk_mul_f32 v[128:129], v[128:129], v[22:23]
	v_pk_mul_f32 v[130:131], v[130:131], v[24:25]
	v_pk_mul_f32 v[132:133], v[132:133], v[26:27]
	v_pk_mul_f32 v[134:135], v[134:135], v[28:29]
	v_pk_mul_f32 v[136:137], v[136:137], v[30:31]
	v_pk_mul_f32 v[138:139], v[138:139], v[32:33]
	v_pk_mul_f32 v[140:141], v[140:141], v[34:35]
	v_pk_mul_f32 v[142:143], v[142:143], v[36:37]
	v_pk_mul_f32 v[144:145], v[144:145], v[38:39]
	v_pk_mul_f32 v[146:147], v[146:147], v[8:9]
	v_pk_mul_f32 v[148:149], v[148:149], v[10:11]
	v_pk_mul_f32 v[150:151], v[150:151], v[12:13]
	v_pk_mul_f32 v[152:153], v[152:153], v[14:15]
	v_pk_mul_f32 v[154:155], v[154:155], v[16:17]
	v_pk_mul_f32 v[156:157], v[156:157], v[18:19]
	v_pk_mul_f32 v[158:159], v[158:159], v[20:21]
	v_pk_mul_f32 v[160:161], v[160:161], v[22:23]
	v_pk_mul_f32 v[162:163], v[162:163], v[24:25]
	v_pk_mul_f32 v[164:165], v[164:165], v[26:27]
	v_pk_mul_f32 v[166:167], v[166:167], v[28:29]
	v_pk_mul_f32 v[168:169], v[168:169], v[30:31]
	v_pk_mul_f32 v[170:171], v[170:171], v[32:33]
	v_pk_mul_f32 v[172:173], v[172:173], v[34:35]
	v_pk_mul_f32 v[174:175], v[174:175], v[36:37]
	v_pk_mul_f32 v[176:177], v[176:177], v[38:39]
	v_cvt_pk_bf16_f32 v82, v114, v115
	v_cvt_pk_bf16_f32 v83, v116, v117
	v_cvt_pk_bf16_f32 v84, v118, v119
	v_cvt_pk_bf16_f32 v85, v120, v121
	v_cvt_pk_bf16_f32 v86, v122, v123
	v_cvt_pk_bf16_f32 v87, v124, v125
	v_cvt_pk_bf16_f32 v88, v126, v127
	v_cvt_pk_bf16_f32 v89, v128, v129
	v_cvt_pk_bf16_f32 v90, v130, v131
	v_cvt_pk_bf16_f32 v91, v132, v133
	v_cvt_pk_bf16_f32 v92, v134, v135
	v_cvt_pk_bf16_f32 v93, v136, v137
	v_cvt_pk_bf16_f32 v94, v138, v139
	v_cvt_pk_bf16_f32 v95, v140, v141
	v_cvt_pk_bf16_f32 v96, v142, v143
	v_cvt_pk_bf16_f32 v97, v144, v145
	v_cvt_pk_bf16_f32 v98, v146, v147
	v_cvt_pk_bf16_f32 v99, v148, v149
	v_cvt_pk_bf16_f32 v100, v150, v151
	v_cvt_pk_bf16_f32 v101, v152, v153
	v_cvt_pk_bf16_f32 v102, v154, v155
	v_cvt_pk_bf16_f32 v103, v156, v157
	v_cvt_pk_bf16_f32 v104, v158, v159
	v_cvt_pk_bf16_f32 v105, v160, v161
	v_cvt_pk_bf16_f32 v106, v162, v163
	v_cvt_pk_bf16_f32 v107, v164, v165
	v_cvt_pk_bf16_f32 v108, v166, v167
	v_cvt_pk_bf16_f32 v109, v168, v169
	v_cvt_pk_bf16_f32 v110, v170, v171
	v_cvt_pk_bf16_f32 v111, v172, v173
	v_cvt_pk_bf16_f32 v112, v174, v175
	v_cvt_pk_bf16_f32 v113, v176, v177
	s_lshl_b32 s23, s10, 12
	s_add_u32 s6, s26, s23
	s_addc_u32 s7, s27, 0
	global_store_dwordx4 v2, v[82:85], s[6:7] offset:0 sc1
	global_store_dwordx4 v2, v[86:89], s[6:7] offset:1024 sc1
	global_store_dwordx4 v2, v[90:93], s[6:7] offset:2048 sc1
	global_store_dwordx4 v2, v[94:97], s[6:7] offset:3072 sc1
	s_add_u32 s6, s6, 0x1000
	s_addc_u32 s7, s7, 0
	global_store_dwordx4 v2, v[98:101], s[6:7] offset:0 sc1
	global_store_dwordx4 v2, v[102:105], s[6:7] offset:1024 sc1
	global_store_dwordx4 v2, v[106:109], s[6:7] offset:2048 sc1
	global_store_dwordx4 v2, v[110:113], s[6:7] offset:3072 sc1
	s_add_u32 s10, s22, 12288
	s_cmp_ge_u32 s10, 0x4400
	s_cselect_b32 s10, s22, s10
	s_lshl_b32 s23, s10, 12
	s_add_u32 s6, s24, s23
	s_addc_u32 s7, s25, 0
	global_load_dwordx4 v[82:85], v2, s[6:7] offset:0
	global_load_dwordx4 v[86:89], v2, s[6:7] offset:1024
	global_load_dwordx4 v[90:93], v2, s[6:7] offset:2048
	global_load_dwordx4 v[94:97], v2, s[6:7] offset:3072
	s_add_u32 s6, s6, 0x1000
	s_addc_u32 s7, s7, 0
	global_load_dwordx4 v[98:101], v2, s[6:7] offset:0
	global_load_dwordx4 v[102:105], v2, s[6:7] offset:1024
	global_load_dwordx4 v[106:109], v2, s[6:7] offset:2048
	global_load_dwordx4 v[110:113], v2, s[6:7] offset:3072
	s_waitcnt vmcnt(16)
	s_add_u32 s22, s22, 8192
	s_cmp_lt_u32 s22, 0x4400
	s_cbranch_scc1 .Lsn_loop
